# opt13
# speedup vs baseline: 1.0221x; 1.0022x over previous
; __device__ __forceinline__ float sigm(float x) { return __builtin_amdgcn_rcpf(1.f + __expf(-x)); }
; __device__ __forceinline__ void gemm_glu_merge(u16* __restrict__ proj, const u16* __restrict__ Wt) {
;     ...
;           const int row = ai * 128 + wr * 64 + m * 16 + fq * 4 + j;
;           u16* pr = proj + (size_t)row * 4096 + nt * 128 + wc * 32 + fr * 2;
;           const float s0 = acc[ai][0][m][0][j] * sigm(acc[ai][0][m][1][j]);
;           const float s1 = acc[ai][1][m][0][j] * sigm(acc[ai][1][m][1][j]);
;           const unsigned at = *(const unsigned*)pr, ga = *(const unsigned*)(pr + 2048), gs = *(const unsigned*)(pr + 3072);
.LBB0_360:
	s_or_b64 exec, exec, s[2:3]
	s_mov_b32 s30, 0xbfb8aa3b
	s_mov_b32 s31, 0xbfb8aa3b
	s_mov_b32 s34, 1.0
	s_mov_b32 s35, 1.0
	v_lshlrev_b32_e32 v128, 6, v132
	v_lshl_add_u32 v128, v135, 2, v128
	v_lshlrev_b32_e32 v128, 13, v128
	s_lshl_b32 s2, s12, 8
	v_lshl_add_u32 v129, v133, 6, s2
	v_lshl_add_u32 v129, v134, 2, v129
	v_add_u32_e32 v137, v128, v129
	s_add_u32 s2, s64, 0x1000
	s_addc_u32 s3, s65, 0
	global_load_dword v138, v137, s[2:3] offset:-4096
	global_load_dword v140, v137, s[2:3]
	global_load_dword v142, v137, s[2:3] offset:2048
	s_add_u32 s2, s64, 0x3000
	s_addc_u32 s3, s65, 0
	global_load_dword v139, v137, s[2:3] offset:-4096
	global_load_dword v141, v137, s[2:3]
	global_load_dword v143, v137, s[2:3] offset:2048
	s_add_u32 s2, s64, 0x5000
	s_addc_u32 s3, s65, 0
	global_load_dword v144, v137, s[2:3] offset:-4096
	global_load_dword v146, v137, s[2:3]
	global_load_dword v148, v137, s[2:3] offset:2048
	s_add_u32 s2, s64, 0x7000
	s_addc_u32 s3, s65, 0
	global_load_dword v145, v137, s[2:3] offset:-4096
	global_load_dword v147, v137, s[2:3]
	global_load_dword v149, v137, s[2:3] offset:2048
	s_add_u32 s2, s64, 0x21000
	s_addc_u32 s3, s65, 0
	global_load_dword v150, v137, s[2:3] offset:-4096
	global_load_dword v152, v137, s[2:3]
	global_load_dword v154, v137, s[2:3] offset:2048
	s_add_u32 s2, s64, 0x23000
	s_addc_u32 s3, s65, 0
	global_load_dword v151, v137, s[2:3] offset:-4096
	global_load_dword v153, v137, s[2:3]
	global_load_dword v155, v137, s[2:3] offset:2048
	s_add_u32 s2, s64, 0x25000
	s_addc_u32 s3, s65, 0
	global_load_dword v156, v137, s[2:3] offset:-4096
	global_load_dword v158, v137, s[2:3]
	global_load_dword v160, v137, s[2:3] offset:2048
	s_add_u32 s2, s64, 0x27000
	s_addc_u32 s3, s65, 0
	global_load_dword v157, v137, s[2:3] offset:-4096
	global_load_dword v159, v137, s[2:3]
	global_load_dword v161, v137, s[2:3] offset:2048
	s_add_u32 s2, s64, 0x41000
	s_addc_u32 s3, s65, 0
	global_load_dword v162, v137, s[2:3] offset:-4096
	global_load_dword v164, v137, s[2:3]
	global_load_dword v166, v137, s[2:3] offset:2048
	s_add_u32 s2, s64, 0x43000
	s_addc_u32 s3, s65, 0
	global_load_dword v163, v137, s[2:3] offset:-4096
	global_load_dword v165, v137, s[2:3]
	global_load_dword v167, v137, s[2:3] offset:2048
	s_add_u32 s2, s64, 0x45000
	s_addc_u32 s3, s65, 0
	global_load_dword v168, v137, s[2:3] offset:-4096
	global_load_dword v170, v137, s[2:3]
	global_load_dword v172, v137, s[2:3] offset:2048
	s_add_u32 s2, s64, 0x47000
	s_addc_u32 s3, s65, 0
	global_load_dword v169, v137, s[2:3] offset:-4096
	global_load_dword v171, v137, s[2:3]
	global_load_dword v173, v137, s[2:3] offset:2048
	s_add_u32 s2, s64, 0x61000
	s_addc_u32 s3, s65, 0
	global_load_dword v174, v137, s[2:3] offset:-4096
	global_load_dword v176, v137, s[2:3]
	global_load_dword v178, v137, s[2:3] offset:2048
	s_add_u32 s2, s64, 0x63000
	s_addc_u32 s3, s65, 0
	global_load_dword v175, v137, s[2:3] offset:-4096
	global_load_dword v177, v137, s[2:3]
	global_load_dword v179, v137, s[2:3] offset:2048
	s_add_u32 s2, s64, 0x65000
	s_addc_u32 s3, s65, 0
	global_load_dword v180, v137, s[2:3] offset:-4096
	global_load_dword v182, v137, s[2:3]
	global_load_dword v184, v137, s[2:3] offset:2048
	s_add_u32 s2, s64, 0x67000
	s_addc_u32 s3, s65, 0
	global_load_dword v181, v137, s[2:3] offset:-4096
	global_load_dword v183, v137, s[2:3]
	global_load_dword v185, v137, s[2:3] offset:2048
	s_add_u32 s2, s64, 0x101000
	s_addc_u32 s3, s65, 0
	global_load_dword v186, v137, s[2:3] offset:-4096
	global_load_dword v188, v137, s[2:3]
	global_load_dword v190, v137, s[2:3] offset:2048
	s_add_u32 s2, s64, 0x103000
	s_addc_u32 s3, s65, 0
	global_load_dword v187, v137, s[2:3] offset:-4096
	global_load_dword v189, v137, s[2:3]
	global_load_dword v191, v137, s[2:3] offset:2048
	s_add_u32 s2, s64, 0x105000
	s_addc_u32 s3, s65, 0
	global_load_dword v192, v137, s[2:3] offset:-4096
	global_load_dword v194, v137, s[2:3]
	global_load_dword v196, v137, s[2:3] offset:2048
	s_add_u32 s2, s64, 0x107000
	s_addc_u32 s3, s65, 0
	global_load_dword v193, v137, s[2:3] offset:-4096
	global_load_dword v195, v137, s[2:3]
	global_load_dword v197, v137, s[2:3] offset:2048
	s_add_u32 s2, s64, 0x121000
	s_addc_u32 s3, s65, 0
	global_load_dword v198, v137, s[2:3] offset:-4096
	global_load_dword v200, v137, s[2:3]
	global_load_dword v202, v137, s[2:3] offset:2048
	s_add_u32 s2, s64, 0x123000
	s_addc_u32 s3, s65, 0
	global_load_dword v199, v137, s[2:3] offset:-4096
	global_load_dword v201, v137, s[2:3]
	global_load_dword v203, v137, s[2:3] offset:2048
	s_add_u32 s2, s64, 0x125000
	s_addc_u32 s3, s65, 0
	global_load_dword v204, v137, s[2:3] offset:-4096
	global_load_dword v206, v137, s[2:3]
	global_load_dword v208, v137, s[2:3] offset:2048
	s_add_u32 s2, s64, 0x127000
	s_addc_u32 s3, s65, 0
	global_load_dword v205, v137, s[2:3] offset:-4096
	global_load_dword v207, v137, s[2:3]
	global_load_dword v209, v137, s[2:3] offset:2048
	s_add_u32 s2, s64, 0x141000
	s_addc_u32 s3, s65, 0
	global_load_dword v210, v137, s[2:3] offset:-4096
	global_load_dword v212, v137, s[2:3]
	global_load_dword v214, v137, s[2:3] offset:2048
	s_add_u32 s2, s64, 0x143000
	s_addc_u32 s3, s65, 0
	global_load_dword v211, v137, s[2:3] offset:-4096
	global_load_dword v213, v137, s[2:3]
	global_load_dword v215, v137, s[2:3] offset:2048
	s_add_u32 s2, s64, 0x145000
	s_addc_u32 s3, s65, 0
	global_load_dword v216, v137, s[2:3] offset:-4096
	global_load_dword v218, v137, s[2:3]
	global_load_dword v220, v137, s[2:3] offset:2048
	s_add_u32 s2, s64, 0x147000
	s_addc_u32 s3, s65, 0
	global_load_dword v217, v137, s[2:3] offset:-4096
	global_load_dword v219, v137, s[2:3]
	global_load_dword v221, v137, s[2:3] offset:2048
	s_add_u32 s2, s64, 0x161000
	s_addc_u32 s3, s65, 0
	global_load_dword v222, v137, s[2:3] offset:-4096
	global_load_dword v224, v137, s[2:3]
	global_load_dword v226, v137, s[2:3] offset:2048
	s_add_u32 s2, s64, 0x163000
	s_addc_u32 s3, s65, 0
	global_load_dword v223, v137, s[2:3] offset:-4096
	global_load_dword v225, v137, s[2:3]
	global_load_dword v227, v137, s[2:3] offset:2048
	s_add_u32 s2, s64, 0x165000
	s_addc_u32 s3, s65, 0
	global_load_dword v228, v137, s[2:3] offset:-4096
	global_load_dword v230, v137, s[2:3]
	global_load_dword v232, v137, s[2:3] offset:2048
	s_add_u32 s2, s64, 0x167000
	s_addc_u32 s3, s65, 0
	global_load_dword v229, v137, s[2:3] offset:-4096
	global_load_dword v231, v137, s[2:3]
	global_load_dword v233, v137, s[2:3] offset:2048
	s_cmp_eq_u32 s12, 7
	s_cbranch_scc1 .Lpf4_skip
; __device__ __forceinline__ float sigm(float x) { return __builtin_amdgcn_rcpf(1.f + __expf(-x)); }
; #define WAIT_V(n) asm volatile("s_waitcnt vmcnt(" #n ")" ::: "memory")
; #define BAR __builtin_amdgcn_s_barrier()
; template <bool PEEL = false>
; __device__ __forceinline__ void gemm_tile(f32x4 (&acc)[2][2][4][2], const u16* __restrict__ A, int lda,
;                                           const u16* __restrict__ B, int K) {
;     ...
;   int rA0, rB0;
;   {
;     int r, c;
;     stage_rc(tid * 16, r, c);
;     rA0 = (r * lda + c) * 2; rB0 = (r * K + c) * 2;
;   }
;   const int wbase = __builtin_amdgcn_readfirstlane(wid) * 1024;
;   const __amdgpu_buffer_rsrc_t rsA = __builtin_amdgcn_make_buffer_rsrc((void*)A, 0, 0x40000000, 0x00020000);
;   const __amdgpu_buffer_rsrc_t rsB = __builtin_amdgcn_make_buffer_rsrc((void*)B, 0, 0x40000000, 0x00020000);
; #pragma unroll
;   for (int a = 0; a < 2; ++a)
; #pragma unroll
;     for (int b = 0; b < 2; ++b)
; #pragma unroll
;       for (int m = 0; m < 4; ++m)
; #pragma unroll
;         for (int n = 0; n < 2; ++n) acc[a][b][m][n] = f32x4{0.f, 0.f, 0.f, 0.f};
;   bf16x8 At[4][2], B0[2][2], B1[2][2];
;   const int nt = K / 64;
;   STAGE_B(SB(0, 0), 0, 0); STAGE_A(SA(0, 0), 0, 0);
;   STAGE_B(SB(0, 1), 1, 0); STAGE_A(SA(0, 1), 1, 0);
;   if (wr == 1) BAR;
;   WAIT_V(4); BAR;
;   STAGE_B(SB(1, 0), 0, 1); STAGE_A(SA(1, 0), 0, 1); STAGE_B(SB(1, 1), 1, 1);
; __device__ __forceinline__ void gemm_glu_merge(u16* __restrict__ proj, const u16* __restrict__ Wt) {
;     ...
;           const float s0 = acc[ai][0][m][0][j] * sigm(acc[ai][0][m][1][j]);
;           const float s1 = acc[ai][1][m][0][j] * sigm(acc[ai][1][m][1][j]);
	v_and_b32_e32 v240, 63, v254
	v_lshlrev_b32_e32 v235, 4, v240
	v_and_b32_e32 v236, 32, v240
	v_xor_b32_e32 v235, v235, v236
	v_lshrrev_b32_e32 v237, 6, v235
	v_and_b32_e32 v235, 63, v235
	v_lshl_add_u32 v235, v237, 13, v235
	v_lshrrev_b32_e32 v237, 6, v254
	v_and_b32_e32 v238, 1, v237
	v_lshl_add_u32 v235, v238, 6, v235
	v_lshrrev_b32_e32 v237, 1, v237
	v_lshl_add_u32 v240, v237, 17, v235
	v_and_b32_e32 v242, 63, v254
	v_lshlrev_b32_e32 v235, 4, v242
	v_and_b32_e32 v236, 32, v242
	v_xor_b32_e32 v235, v235, v236
	v_lshrrev_b32_e32 v237, 6, v235
	v_and_b32_e32 v235, 63, v235
	v_lshl_add_u32 v235, v237, 10, v235
	v_lshrrev_b32_e32 v237, 6, v254
	v_and_b32_e32 v238, 1, v237
	v_lshl_add_u32 v235, v238, 6, v235
	v_lshrrev_b32_e32 v237, 1, v237
	v_lshl_add_u32 v242, v237, 14, v235
	s_add_i32 s2, s12, 1
	s_lshl_b32 s2, s2, 18
	s_add_u32 s8, s0, s2
	s_addc_u32 s9, s1, 0
	s_and_b32 s9, s9, 0xffff
	s_mov_b32 s10, s6
	s_mov_b32 s11, s7
	s_mov_b32 m0, s45
	s_nop 0
	buffer_load_dwordx4 v242, s[8:11], 0 offen lds
	s_mov_b32 m0, s46
	s_nop 0
	buffer_load_dwordx4 v242, s[8:11], s14 offen lds
	s_mov_b32 m0, s44
	s_nop 0
	buffer_load_dwordx4 v240, s[4:7], 0 offen lds
	s_mov_b32 m0, s47
	s_nop 0
	buffer_load_dwordx4 v240, s[4:7], s15 offen lds
	s_mov_b32 m0, s48
	s_nop 0
	buffer_load_dwordx4 v242, s[8:11], s7 offen lds
	s_mov_b32 m0, s49
	s_nop 0
	buffer_load_dwordx4 v242, s[8:11], s16 offen lds
	s_mov_b32 m0, s52
	s_nop 0
	buffer_load_dwordx4 v240, s[4:7], s17 offen lds
	s_mov_b32 m0, s53
	s_nop 0
	buffer_load_dwordx4 v240, s[4:7], s18 offen lds
	s_add_i32 m0, s44, 0x18000
	s_nop 0
	buffer_load_dwordx4 v242, s[8:11], s19 offen lds
	s_add_i32 m0, s44, 0x1a000
	s_nop 0
	buffer_load_dwordx4 v242, s[8:11], s20 offen lds
	s_mov_b32 m0, s66
	s_nop 0
	buffer_load_dwordx4 v240, s[4:7], s19 offen lds
	s_mov_b32 m0, s67
	s_nop 0
	buffer_load_dwordx4 v240, s[4:7], s21 offen lds
	s_mov_b32 m0, s78
	s_nop 0
	buffer_load_dwordx4 v242, s[8:11], s22 offen lds
	s_mov_b32 m0, s79
	s_nop 0
	buffer_load_dwordx4 v242, s[8:11], s23 offen lds
.Lpf4_skip:
	v_pk_mul_f32 v[120:121], v[120:121], s[30:31]
	v_pk_mul_f32 v[124:125], v[124:125], s[30:31]
	v_pk_mul_f32 v[122:123], v[122:123], s[30:31]
	v_pk_mul_f32 v[126:127], v[126:127], s[30:31]
	v_exp_f32_e32 v120, v120
	v_exp_f32_e32 v121, v121
	v_exp_f32_e32 v124, v124
	v_exp_f32_e32 v125, v125
	v_exp_f32_e32 v122, v122
	v_exp_f32_e32 v123, v123
	v_exp_f32_e32 v126, v126
	v_exp_f32_e32 v127, v127
	v_pk_add_f32 v[120:121], v[120:121], s[34:35]
	v_pk_add_f32 v[124:125], v[124:125], s[34:35]
	v_pk_add_f32 v[122:123], v[122:123], s[34:35]
	v_pk_add_f32 v[126:127], v[126:127], s[34:35]
	v_rcp_f32_e32 v120, v120
	v_rcp_f32_e32 v121, v121
	v_rcp_f32_e32 v124, v124
	v_rcp_f32_e32 v125, v125
	v_rcp_f32_e32 v122, v122
	v_rcp_f32_e32 v123, v123
	v_rcp_f32_e32 v126, v126
	v_rcp_f32_e32 v127, v127
	v_pk_mul_f32 v[112:113], v[112:113], v[120:121]
	v_pk_mul_f32 v[116:117], v[116:117], v[124:125]
	v_pk_mul_f32 v[114:115], v[114:115], v[122:123]
	v_pk_mul_f32 v[118:119], v[118:119], v[126:127]
	v_pk_mul_f32 v[104:105], v[104:105], s[30:31]
	v_pk_mul_f32 v[108:109], v[108:109], s[30:31]
	v_pk_mul_f32 v[106:107], v[106:107], s[30:31]
	v_pk_mul_f32 v[110:111], v[110:111], s[30:31]
	v_exp_f32_e32 v104, v104
	v_exp_f32_e32 v105, v105
	v_exp_f32_e32 v108, v108
	v_exp_f32_e32 v109, v109
	v_exp_f32_e32 v106, v106
	v_exp_f32_e32 v107, v107
	v_exp_f32_e32 v110, v110
	v_exp_f32_e32 v111, v111
	v_pk_add_f32 v[104:105], v[104:105], s[34:35]
	v_pk_add_f32 v[108:109], v[108:109], s[34:35]
	v_pk_add_f32 v[106:107], v[106:107], s[34:35]
	v_pk_add_f32 v[110:111], v[110:111], s[34:35]
	v_rcp_f32_e32 v104, v104
	v_rcp_f32_e32 v105, v105
	v_rcp_f32_e32 v108, v108
	v_rcp_f32_e32 v109, v109
	v_rcp_f32_e32 v106, v106
	v_rcp_f32_e32 v107, v107
	v_rcp_f32_e32 v110, v110
	v_rcp_f32_e32 v111, v111
	v_pk_mul_f32 v[96:97], v[96:97], v[104:105]
	v_pk_mul_f32 v[100:101], v[100:101], v[108:109]
	v_pk_mul_f32 v[98:99], v[98:99], v[106:107]
	v_pk_mul_f32 v[102:103], v[102:103], v[110:111]
	v_pk_mul_f32 v[88:89], v[88:89], s[30:31]
	v_pk_mul_f32 v[92:93], v[92:93], s[30:31]
	v_pk_mul_f32 v[90:91], v[90:91], s[30:31]
	v_pk_mul_f32 v[94:95], v[94:95], s[30:31]
	v_exp_f32_e32 v88, v88
	v_exp_f32_e32 v89, v89
	v_exp_f32_e32 v92, v92
	v_exp_f32_e32 v93, v93
	v_exp_f32_e32 v90, v90
	v_exp_f32_e32 v91, v91
	v_exp_f32_e32 v94, v94
	v_exp_f32_e32 v95, v95
	v_pk_add_f32 v[88:89], v[88:89], s[34:35]
	v_pk_add_f32 v[92:93], v[92:93], s[34:35]
	v_pk_add_f32 v[90:91], v[90:91], s[34:35]
	v_pk_add_f32 v[94:95], v[94:95], s[34:35]
	v_rcp_f32_e32 v88, v88
	v_rcp_f32_e32 v89, v89
	v_rcp_f32_e32 v92, v92
	v_rcp_f32_e32 v93, v93
	v_rcp_f32_e32 v90, v90
	v_rcp_f32_e32 v91, v91
	v_rcp_f32_e32 v94, v94
	v_rcp_f32_e32 v95, v95
	v_pk_mul_f32 v[80:81], v[80:81], v[88:89]
	v_pk_mul_f32 v[84:85], v[84:85], v[92:93]
	v_pk_mul_f32 v[82:83], v[82:83], v[90:91]
	v_pk_mul_f32 v[86:87], v[86:87], v[94:95]
	v_pk_mul_f32 v[72:73], v[72:73], s[30:31]
	v_pk_mul_f32 v[76:77], v[76:77], s[30:31]
	v_pk_mul_f32 v[74:75], v[74:75], s[30:31]
	v_pk_mul_f32 v[78:79], v[78:79], s[30:31]
	v_exp_f32_e32 v72, v72
	v_exp_f32_e32 v73, v73
	v_exp_f32_e32 v76, v76
	v_exp_f32_e32 v77, v77
	v_exp_f32_e32 v74, v74
	v_exp_f32_e32 v75, v75
	v_exp_f32_e32 v78, v78
	v_exp_f32_e32 v79, v79
	v_pk_add_f32 v[72:73], v[72:73], s[34:35]
	v_pk_add_f32 v[76:77], v[76:77], s[34:35]
	v_pk_add_f32 v[74:75], v[74:75], s[34:35]
	v_pk_add_f32 v[78:79], v[78:79], s[34:35]
	v_rcp_f32_e32 v72, v72
	v_rcp_f32_e32 v73, v73
	v_rcp_f32_e32 v76, v76
	v_rcp_f32_e32 v77, v77
	v_rcp_f32_e32 v74, v74
	v_rcp_f32_e32 v75, v75
	v_rcp_f32_e32 v78, v78
	v_rcp_f32_e32 v79, v79
; __device__ __forceinline__ float sigm(float x) { return __builtin_amdgcn_rcpf(1.f + __expf(-x)); }
; __device__ __forceinline__ void gemm_glu_merge(u16* __restrict__ proj, const u16* __restrict__ Wt) {
;     ...
;           const float s0 = acc[ai][0][m][0][j] * sigm(acc[ai][0][m][1][j]);
;           const float s1 = acc[ai][1][m][0][j] * sigm(acc[ai][1][m][1][j]);
;           const unsigned at = *(const unsigned*)pr, ga = *(const unsigned*)(pr + 2048), gs = *(const unsigned*)(pr + 3072);
;           const float m0 = sigm(__uint_as_float(ga << 16)) * __uint_as_float(at << 16) + sigm(__uint_as_float(gs << 16)) * s0;
;           const float m1 = sigm(__uint_as_float(ga & 0xffff0000u)) * __uint_as_float(at & 0xffff0000u) +
;                            sigm(__uint_as_float(gs & 0xffff0000u)) * s1;
;           __builtin_nontemporal_store(pack2(m0, m1), (unsigned*)pr);
	v_pk_mul_f32 v[64:65], v[64:65], v[72:73]
	v_pk_mul_f32 v[68:69], v[68:69], v[76:77]
	v_pk_mul_f32 v[66:67], v[66:67], v[74:75]
	v_pk_mul_f32 v[70:71], v[70:71], v[78:79]
	v_pk_mul_f32 v[56:57], v[56:57], s[30:31]
	v_pk_mul_f32 v[60:61], v[60:61], s[30:31]
	v_pk_mul_f32 v[58:59], v[58:59], s[30:31]
	v_pk_mul_f32 v[62:63], v[62:63], s[30:31]
	v_exp_f32_e32 v56, v56
	v_exp_f32_e32 v57, v57
	v_exp_f32_e32 v60, v60
	v_exp_f32_e32 v61, v61
	v_exp_f32_e32 v58, v58
	v_exp_f32_e32 v59, v59
	v_exp_f32_e32 v62, v62
	v_exp_f32_e32 v63, v63
	v_pk_add_f32 v[56:57], v[56:57], s[34:35]
	v_pk_add_f32 v[60:61], v[60:61], s[34:35]
	v_pk_add_f32 v[58:59], v[58:59], s[34:35]
	v_pk_add_f32 v[62:63], v[62:63], s[34:35]
	v_rcp_f32_e32 v56, v56
	v_rcp_f32_e32 v57, v57
	v_rcp_f32_e32 v60, v60
	v_rcp_f32_e32 v61, v61
	v_rcp_f32_e32 v58, v58
	v_rcp_f32_e32 v59, v59
	v_rcp_f32_e32 v62, v62
	v_rcp_f32_e32 v63, v63
	v_pk_mul_f32 v[48:49], v[48:49], v[56:57]
	v_pk_mul_f32 v[52:53], v[52:53], v[60:61]
	v_pk_mul_f32 v[50:51], v[50:51], v[58:59]
	v_pk_mul_f32 v[54:55], v[54:55], v[62:63]
	v_pk_mul_f32 v[40:41], v[40:41], s[30:31]
	v_pk_mul_f32 v[44:45], v[44:45], s[30:31]
	v_pk_mul_f32 v[42:43], v[42:43], s[30:31]
	v_pk_mul_f32 v[46:47], v[46:47], s[30:31]
	v_exp_f32_e32 v40, v40
	v_exp_f32_e32 v41, v41
	v_exp_f32_e32 v44, v44
	v_exp_f32_e32 v45, v45
	v_exp_f32_e32 v42, v42
	v_exp_f32_e32 v43, v43
	v_exp_f32_e32 v46, v46
	v_exp_f32_e32 v47, v47
	v_pk_add_f32 v[40:41], v[40:41], s[34:35]
	v_pk_add_f32 v[44:45], v[44:45], s[34:35]
	v_pk_add_f32 v[42:43], v[42:43], s[34:35]
	v_pk_add_f32 v[46:47], v[46:47], s[34:35]
	v_rcp_f32_e32 v40, v40
	v_rcp_f32_e32 v41, v41
	v_rcp_f32_e32 v44, v44
	v_rcp_f32_e32 v45, v45
	v_rcp_f32_e32 v42, v42
	v_rcp_f32_e32 v43, v43
	v_rcp_f32_e32 v46, v46
	v_rcp_f32_e32 v47, v47
	v_pk_mul_f32 v[32:33], v[32:33], v[40:41]
	v_pk_mul_f32 v[36:37], v[36:37], v[44:45]
	v_pk_mul_f32 v[34:35], v[34:35], v[42:43]
	v_pk_mul_f32 v[38:39], v[38:39], v[46:47]
	v_pk_mul_f32 v[24:25], v[24:25], s[30:31]
	v_pk_mul_f32 v[28:29], v[28:29], s[30:31]
	v_pk_mul_f32 v[26:27], v[26:27], s[30:31]
	v_pk_mul_f32 v[30:31], v[30:31], s[30:31]
	v_exp_f32_e32 v24, v24
	v_exp_f32_e32 v25, v25
	v_exp_f32_e32 v28, v28
	v_exp_f32_e32 v29, v29
	v_exp_f32_e32 v26, v26
	v_exp_f32_e32 v27, v27
	v_exp_f32_e32 v30, v30
	v_exp_f32_e32 v31, v31
	v_pk_add_f32 v[24:25], v[24:25], s[34:35]
	v_pk_add_f32 v[28:29], v[28:29], s[34:35]
	v_pk_add_f32 v[26:27], v[26:27], s[34:35]
	v_pk_add_f32 v[30:31], v[30:31], s[34:35]
	v_rcp_f32_e32 v24, v24
	v_rcp_f32_e32 v25, v25
	v_rcp_f32_e32 v28, v28
	v_rcp_f32_e32 v29, v29
	v_rcp_f32_e32 v26, v26
	v_rcp_f32_e32 v27, v27
	v_rcp_f32_e32 v30, v30
	v_rcp_f32_e32 v31, v31
	v_pk_mul_f32 v[16:17], v[16:17], v[24:25]
	v_pk_mul_f32 v[20:21], v[20:21], v[28:29]
	v_pk_mul_f32 v[18:19], v[18:19], v[26:27]
	v_pk_mul_f32 v[22:23], v[22:23], v[30:31]
	v_pk_mul_f32 v[8:9], v[8:9], s[30:31]
	v_pk_mul_f32 v[12:13], v[12:13], s[30:31]
	v_pk_mul_f32 v[10:11], v[10:11], s[30:31]
	v_pk_mul_f32 v[14:15], v[14:15], s[30:31]
	v_exp_f32_e32 v8, v8
	v_exp_f32_e32 v9, v9
	v_exp_f32_e32 v12, v12
	v_exp_f32_e32 v13, v13
	v_exp_f32_e32 v10, v10
	v_exp_f32_e32 v11, v11
	v_exp_f32_e32 v14, v14
	v_exp_f32_e32 v15, v15
	v_pk_add_f32 v[8:9], v[8:9], s[34:35]
	v_pk_add_f32 v[12:13], v[12:13], s[34:35]
	v_pk_add_f32 v[10:11], v[10:11], s[34:35]
	v_pk_add_f32 v[14:15], v[14:15], s[34:35]
	v_rcp_f32_e32 v8, v8
	v_rcp_f32_e32 v9, v9
	v_rcp_f32_e32 v12, v12
	v_rcp_f32_e32 v13, v13
	v_rcp_f32_e32 v10, v10
	v_rcp_f32_e32 v11, v11
	v_rcp_f32_e32 v14, v14
	v_rcp_f32_e32 v15, v15
	v_pk_mul_f32 v[0:1], v[0:1], v[8:9]
	v_pk_mul_f32 v[4:5], v[4:5], v[12:13]
	v_pk_mul_f32 v[2:3], v[2:3], v[10:11]
	v_pk_mul_f32 v[6:7], v[6:7], v[14:15]
	s_waitcnt vmcnt(63)
	v_lshlrev_b32_e32 v238, 16, v138
	v_lshlrev_b32_e32 v239, 16, v139
	v_lshlrev_b32_e32 v240, 16, v140
	v_lshlrev_b32_e32 v241, 16, v141
	v_lshlrev_b32_e32 v242, 16, v142
	v_lshlrev_b32_e32 v243, 16, v143
	v_and_b32_e32 v138, 0xffff0000, v138
	v_and_b32_e32 v139, 0xffff0000, v139
	v_and_b32_e32 v140, 0xffff0000, v140
	v_and_b32_e32 v141, 0xffff0000, v141
	v_and_b32_e32 v142, 0xffff0000, v142
	v_and_b32_e32 v143, 0xffff0000, v143
	v_pk_mul_f32 v[240:241], v[240:241], s[30:31]
	v_pk_mul_f32 v[140:141], v[140:141], s[30:31]
	v_pk_mul_f32 v[242:243], v[242:243], s[30:31]
	v_pk_mul_f32 v[142:143], v[142:143], s[30:31]
	v_exp_f32_e32 v240, v240
	v_exp_f32_e32 v241, v241
	v_exp_f32_e32 v140, v140
	v_exp_f32_e32 v141, v141
	v_exp_f32_e32 v242, v242
	v_exp_f32_e32 v243, v243
	v_exp_f32_e32 v142, v142
	v_exp_f32_e32 v143, v143
	v_pk_add_f32 v[240:241], v[240:241], s[34:35]
	v_pk_add_f32 v[140:141], v[140:141], s[34:35]
	v_pk_add_f32 v[242:243], v[242:243], s[34:35]
	v_pk_add_f32 v[142:143], v[142:143], s[34:35]
	v_rcp_f32_e32 v240, v240
	v_rcp_f32_e32 v241, v241
	v_rcp_f32_e32 v140, v140
	v_rcp_f32_e32 v141, v141
	v_rcp_f32_e32 v242, v242
	v_rcp_f32_e32 v243, v243
	v_rcp_f32_e32 v142, v142
	v_rcp_f32_e32 v143, v143
	v_pk_mul_f32 v[238:239], v[240:241], v[238:239]
	v_pk_mul_f32 v[138:139], v[140:141], v[138:139]
	v_pk_fma_f32 v[238:239], v[242:243], v[112:113], v[238:239]
	v_pk_fma_f32 v[138:139], v[142:143], v[116:117], v[138:139]
	v_cvt_pk_bf16_f32 v240, v238, v138
	v_cvt_pk_bf16_f32 v241, v239, v139
	s_add_u32 s2, s64, 0x1000
	s_addc_u32 s3, s65, 0
	global_store_dword v137, v240, s[2:3] offset:-4096 nt
	s_add_u32 s2, s64, 0x3000
	s_addc_u32 s3, s65, 0
	global_store_dword v137, v241, s[2:3] offset:-4096 nt
	s_waitcnt vmcnt(63)
; __device__ __forceinline__ float sigm(float x) { return __builtin_amdgcn_rcpf(1.f + __expf(-x)); }
; __device__ __forceinline__ void gemm_glu_merge(u16* __restrict__ proj, const u16* __restrict__ Wt) {
;     ...
;           const int row = ai * 128 + wr * 64 + m * 16 + fq * 4 + j;
;           u16* pr = proj + (size_t)row * 4096 + nt * 128 + wc * 32 + fr * 2;
;           const float s0 = acc[ai][0][m][0][j] * sigm(acc[ai][0][m][1][j]);
;           const float s1 = acc[ai][1][m][0][j] * sigm(acc[ai][1][m][1][j]);
;           const unsigned at = *(const unsigned*)pr, ga = *(const unsigned*)(pr + 2048), gs = *(const unsigned*)(pr + 3072);
;           const float m0 = sigm(__uint_as_float(ga << 16)) * __uint_as_float(at << 16) + sigm(__uint_as_float(gs << 16)) * s0;
;           const float m1 = sigm(__uint_as_float(ga & 0xffff0000u)) * __uint_as_float(at & 0xffff0000u) +
;                            sigm(__uint_as_float(gs & 0xffff0000u)) * s1;
;           __builtin_nontemporal_store(pack2(m0, m1), (unsigned*)pr);
	v_lshlrev_b32_e32 v248, 16, v144
	v_lshlrev_b32_e32 v249, 16, v145
	v_lshlrev_b32_e32 v250, 16, v146
	v_lshlrev_b32_e32 v251, 16, v147
	v_lshlrev_b32_e32 v252, 16, v148
	v_lshlrev_b32_e32 v253, 16, v149
	v_and_b32_e32 v144, 0xffff0000, v144
	v_and_b32_e32 v145, 0xffff0000, v145
	v_and_b32_e32 v146, 0xffff0000, v146
	v_and_b32_e32 v147, 0xffff0000, v147
	v_and_b32_e32 v148, 0xffff0000, v148
	v_and_b32_e32 v149, 0xffff0000, v149
	v_pk_mul_f32 v[250:251], v[250:251], s[30:31]
	v_pk_mul_f32 v[146:147], v[146:147], s[30:31]
	v_pk_mul_f32 v[252:253], v[252:253], s[30:31]
	v_pk_mul_f32 v[148:149], v[148:149], s[30:31]
	v_exp_f32_e32 v250, v250
	v_exp_f32_e32 v251, v251
	v_exp_f32_e32 v146, v146
	v_exp_f32_e32 v147, v147
	v_exp_f32_e32 v252, v252
	v_exp_f32_e32 v253, v253
	v_exp_f32_e32 v148, v148
	v_exp_f32_e32 v149, v149
	v_pk_add_f32 v[250:251], v[250:251], s[34:35]
	v_pk_add_f32 v[146:147], v[146:147], s[34:35]
	v_pk_add_f32 v[252:253], v[252:253], s[34:35]
	v_pk_add_f32 v[148:149], v[148:149], s[34:35]
	v_rcp_f32_e32 v250, v250
	v_rcp_f32_e32 v251, v251
	v_rcp_f32_e32 v146, v146
	v_rcp_f32_e32 v147, v147
	v_rcp_f32_e32 v252, v252
	v_rcp_f32_e32 v253, v253
	v_rcp_f32_e32 v148, v148
	v_rcp_f32_e32 v149, v149
	v_pk_mul_f32 v[248:249], v[250:251], v[248:249]
	v_pk_mul_f32 v[144:145], v[146:147], v[144:145]
	v_pk_fma_f32 v[248:249], v[252:253], v[114:115], v[248:249]
	v_pk_fma_f32 v[144:145], v[148:149], v[118:119], v[144:145]
	v_cvt_pk_bf16_f32 v250, v248, v144
	v_cvt_pk_bf16_f32 v251, v249, v145
	s_add_u32 s2, s64, 0x5000
	s_addc_u32 s3, s65, 0
	global_store_dword v137, v250, s[2:3] offset:-4096 nt
	s_add_u32 s2, s64, 0x7000
	s_addc_u32 s3, s65, 0
	global_store_dword v137, v251, s[2:3] offset:-4096 nt
	s_waitcnt vmcnt(63)
	v_lshlrev_b32_e32 v238, 16, v150
	v_lshlrev_b32_e32 v239, 16, v151
	v_lshlrev_b32_e32 v240, 16, v152
	v_lshlrev_b32_e32 v241, 16, v153
	v_lshlrev_b32_e32 v242, 16, v154
	v_lshlrev_b32_e32 v243, 16, v155
	v_and_b32_e32 v150, 0xffff0000, v150
	v_and_b32_e32 v151, 0xffff0000, v151
	v_and_b32_e32 v152, 0xffff0000, v152
	v_and_b32_e32 v153, 0xffff0000, v153
	v_and_b32_e32 v154, 0xffff0000, v154
	v_and_b32_e32 v155, 0xffff0000, v155
	v_pk_mul_f32 v[240:241], v[240:241], s[30:31]
	v_pk_mul_f32 v[152:153], v[152:153], s[30:31]
	v_pk_mul_f32 v[242:243], v[242:243], s[30:31]
	v_pk_mul_f32 v[154:155], v[154:155], s[30:31]
	v_exp_f32_e32 v240, v240
	v_exp_f32_e32 v241, v241
	v_exp_f32_e32 v152, v152
	v_exp_f32_e32 v153, v153
	v_exp_f32_e32 v242, v242
	v_exp_f32_e32 v243, v243
	v_exp_f32_e32 v154, v154
	v_exp_f32_e32 v155, v155
	v_pk_add_f32 v[240:241], v[240:241], s[34:35]
	v_pk_add_f32 v[152:153], v[152:153], s[34:35]
	v_pk_add_f32 v[242:243], v[242:243], s[34:35]
	v_pk_add_f32 v[154:155], v[154:155], s[34:35]
	v_rcp_f32_e32 v240, v240
	v_rcp_f32_e32 v241, v241
	v_rcp_f32_e32 v152, v152
	v_rcp_f32_e32 v153, v153
	v_rcp_f32_e32 v242, v242
	v_rcp_f32_e32 v243, v243
	v_rcp_f32_e32 v154, v154
	v_rcp_f32_e32 v155, v155
	v_pk_mul_f32 v[238:239], v[240:241], v[238:239]
	v_pk_mul_f32 v[150:151], v[152:153], v[150:151]
	v_pk_fma_f32 v[238:239], v[242:243], v[96:97], v[238:239]
	v_pk_fma_f32 v[150:151], v[154:155], v[100:101], v[150:151]
	v_cvt_pk_bf16_f32 v240, v238, v150
	v_cvt_pk_bf16_f32 v241, v239, v151
	s_add_u32 s2, s64, 0x21000
	s_addc_u32 s3, s65, 0
	global_store_dword v137, v240, s[2:3] offset:-4096 nt
	s_add_u32 s2, s64, 0x23000
	s_addc_u32 s3, s65, 0
	global_store_dword v137, v241, s[2:3] offset:-4096 nt
	s_waitcnt vmcnt(63)
	v_lshlrev_b32_e32 v248, 16, v156
	v_lshlrev_b32_e32 v249, 16, v157
	v_lshlrev_b32_e32 v250, 16, v158
	v_lshlrev_b32_e32 v251, 16, v159
	v_lshlrev_b32_e32 v252, 16, v160
	v_lshlrev_b32_e32 v253, 16, v161
	v_and_b32_e32 v156, 0xffff0000, v156
	v_and_b32_e32 v157, 0xffff0000, v157
	v_and_b32_e32 v158, 0xffff0000, v158
	v_and_b32_e32 v159, 0xffff0000, v159
	v_and_b32_e32 v160, 0xffff0000, v160
	v_and_b32_e32 v161, 0xffff0000, v161
	v_pk_mul_f32 v[250:251], v[250:251], s[30:31]
	v_pk_mul_f32 v[158:159], v[158:159], s[30:31]
	v_pk_mul_f32 v[252:253], v[252:253], s[30:31]
	v_pk_mul_f32 v[160:161], v[160:161], s[30:31]
	v_exp_f32_e32 v250, v250
	v_exp_f32_e32 v251, v251
	v_exp_f32_e32 v158, v158
	v_exp_f32_e32 v159, v159
	v_exp_f32_e32 v252, v252
	v_exp_f32_e32 v253, v253
	v_exp_f32_e32 v160, v160
	v_exp_f32_e32 v161, v161
	v_pk_add_f32 v[250:251], v[250:251], s[34:35]
	v_pk_add_f32 v[158:159], v[158:159], s[34:35]
	v_pk_add_f32 v[252:253], v[252:253], s[34:35]
	v_pk_add_f32 v[160:161], v[160:161], s[34:35]
	v_rcp_f32_e32 v250, v250
	v_rcp_f32_e32 v251, v251
	v_rcp_f32_e32 v158, v158
	v_rcp_f32_e32 v159, v159
	v_rcp_f32_e32 v252, v252
	v_rcp_f32_e32 v253, v253
	v_rcp_f32_e32 v160, v160
	v_rcp_f32_e32 v161, v161
	v_pk_mul_f32 v[248:249], v[250:251], v[248:249]
	v_pk_mul_f32 v[156:157], v[158:159], v[156:157]
	v_pk_fma_f32 v[248:249], v[252:253], v[98:99], v[248:249]
	v_pk_fma_f32 v[156:157], v[160:161], v[102:103], v[156:157]
	v_cvt_pk_bf16_f32 v250, v248, v156
	v_cvt_pk_bf16_f32 v251, v249, v157
	s_add_u32 s2, s64, 0x25000
	s_addc_u32 s3, s65, 0
	global_store_dword v137, v250, s[2:3] offset:-4096 nt
	s_add_u32 s2, s64, 0x27000
	s_addc_u32 s3, s65, 0
	global_store_dword v137, v251, s[2:3] offset:-4096 nt
	s_waitcnt vmcnt(63)
; __device__ __forceinline__ float sigm(float x) { return __builtin_amdgcn_rcpf(1.f + __expf(-x)); }
; __device__ __forceinline__ void gemm_glu_merge(u16* __restrict__ proj, const u16* __restrict__ Wt) {
;     ...
;           const int row = ai * 128 + wr * 64 + m * 16 + fq * 4 + j;
;           u16* pr = proj + (size_t)row * 4096 + nt * 128 + wc * 32 + fr * 2;
;           const float s0 = acc[ai][0][m][0][j] * sigm(acc[ai][0][m][1][j]);
;           const float s1 = acc[ai][1][m][0][j] * sigm(acc[ai][1][m][1][j]);
;           const unsigned at = *(const unsigned*)pr, ga = *(const unsigned*)(pr + 2048), gs = *(const unsigned*)(pr + 3072);
;           const float m0 = sigm(__uint_as_float(ga << 16)) * __uint_as_float(at << 16) + sigm(__uint_as_float(gs << 16)) * s0;
;           const float m1 = sigm(__uint_as_float(ga & 0xffff0000u)) * __uint_as_float(at & 0xffff0000u) +
;                            sigm(__uint_as_float(gs & 0xffff0000u)) * s1;
;           __builtin_nontemporal_store(pack2(m0, m1), (unsigned*)pr);
	v_lshlrev_b32_e32 v238, 16, v162
	v_lshlrev_b32_e32 v239, 16, v163
	v_lshlrev_b32_e32 v240, 16, v164
	v_lshlrev_b32_e32 v241, 16, v165
	v_lshlrev_b32_e32 v242, 16, v166
	v_lshlrev_b32_e32 v243, 16, v167
	v_and_b32_e32 v162, 0xffff0000, v162
	v_and_b32_e32 v163, 0xffff0000, v163
	v_and_b32_e32 v164, 0xffff0000, v164
	v_and_b32_e32 v165, 0xffff0000, v165
	v_and_b32_e32 v166, 0xffff0000, v166
	v_and_b32_e32 v167, 0xffff0000, v167
	v_pk_mul_f32 v[240:241], v[240:241], s[30:31]
	v_pk_mul_f32 v[164:165], v[164:165], s[30:31]
	v_pk_mul_f32 v[242:243], v[242:243], s[30:31]
	v_pk_mul_f32 v[166:167], v[166:167], s[30:31]
	v_exp_f32_e32 v240, v240
	v_exp_f32_e32 v241, v241
	v_exp_f32_e32 v164, v164
	v_exp_f32_e32 v165, v165
	v_exp_f32_e32 v242, v242
	v_exp_f32_e32 v243, v243
	v_exp_f32_e32 v166, v166
	v_exp_f32_e32 v167, v167
	v_pk_add_f32 v[240:241], v[240:241], s[34:35]
	v_pk_add_f32 v[164:165], v[164:165], s[34:35]
	v_pk_add_f32 v[242:243], v[242:243], s[34:35]
	v_pk_add_f32 v[166:167], v[166:167], s[34:35]
	v_rcp_f32_e32 v240, v240
	v_rcp_f32_e32 v241, v241
	v_rcp_f32_e32 v164, v164
	v_rcp_f32_e32 v165, v165
	v_rcp_f32_e32 v242, v242
	v_rcp_f32_e32 v243, v243
	v_rcp_f32_e32 v166, v166
	v_rcp_f32_e32 v167, v167
	v_pk_mul_f32 v[238:239], v[240:241], v[238:239]
	v_pk_mul_f32 v[162:163], v[164:165], v[162:163]
	v_pk_fma_f32 v[238:239], v[242:243], v[80:81], v[238:239]
	v_pk_fma_f32 v[162:163], v[166:167], v[84:85], v[162:163]
	v_cvt_pk_bf16_f32 v240, v238, v162
	v_cvt_pk_bf16_f32 v241, v239, v163
	s_add_u32 s2, s64, 0x41000
	s_addc_u32 s3, s65, 0
	global_store_dword v137, v240, s[2:3] offset:-4096 nt
	s_add_u32 s2, s64, 0x43000
	s_addc_u32 s3, s65, 0
	global_store_dword v137, v241, s[2:3] offset:-4096 nt
	s_waitcnt vmcnt(63)
	v_lshlrev_b32_e32 v248, 16, v168
	v_lshlrev_b32_e32 v249, 16, v169
	v_lshlrev_b32_e32 v250, 16, v170
	v_lshlrev_b32_e32 v251, 16, v171
	v_lshlrev_b32_e32 v252, 16, v172
	v_lshlrev_b32_e32 v253, 16, v173
	v_and_b32_e32 v168, 0xffff0000, v168
	v_and_b32_e32 v169, 0xffff0000, v169
	v_and_b32_e32 v170, 0xffff0000, v170
	v_and_b32_e32 v171, 0xffff0000, v171
	v_and_b32_e32 v172, 0xffff0000, v172
	v_and_b32_e32 v173, 0xffff0000, v173
	v_pk_mul_f32 v[250:251], v[250:251], s[30:31]
	v_pk_mul_f32 v[170:171], v[170:171], s[30:31]
	v_pk_mul_f32 v[252:253], v[252:253], s[30:31]
	v_pk_mul_f32 v[172:173], v[172:173], s[30:31]
	v_exp_f32_e32 v250, v250
	v_exp_f32_e32 v251, v251
	v_exp_f32_e32 v170, v170
	v_exp_f32_e32 v171, v171
	v_exp_f32_e32 v252, v252
	v_exp_f32_e32 v253, v253
	v_exp_f32_e32 v172, v172
	v_exp_f32_e32 v173, v173
	v_pk_add_f32 v[250:251], v[250:251], s[34:35]
	v_pk_add_f32 v[170:171], v[170:171], s[34:35]
	v_pk_add_f32 v[252:253], v[252:253], s[34:35]
	v_pk_add_f32 v[172:173], v[172:173], s[34:35]
	v_rcp_f32_e32 v250, v250
	v_rcp_f32_e32 v251, v251
	v_rcp_f32_e32 v170, v170
	v_rcp_f32_e32 v171, v171
	v_rcp_f32_e32 v252, v252
	v_rcp_f32_e32 v253, v253
	v_rcp_f32_e32 v172, v172
	v_rcp_f32_e32 v173, v173
	v_pk_mul_f32 v[248:249], v[250:251], v[248:249]
	v_pk_mul_f32 v[168:169], v[170:171], v[168:169]
	v_pk_fma_f32 v[248:249], v[252:253], v[82:83], v[248:249]
	v_pk_fma_f32 v[168:169], v[172:173], v[86:87], v[168:169]
	v_cvt_pk_bf16_f32 v250, v248, v168
	v_cvt_pk_bf16_f32 v251, v249, v169
	s_add_u32 s2, s64, 0x45000
	s_addc_u32 s3, s65, 0
	global_store_dword v137, v250, s[2:3] offset:-4096 nt
	s_add_u32 s2, s64, 0x47000
	s_addc_u32 s3, s65, 0
	global_store_dword v137, v251, s[2:3] offset:-4096 nt
	s_waitcnt vmcnt(63)
	v_lshlrev_b32_e32 v238, 16, v174
	v_lshlrev_b32_e32 v239, 16, v175
	v_lshlrev_b32_e32 v240, 16, v176
	v_lshlrev_b32_e32 v241, 16, v177
	v_lshlrev_b32_e32 v242, 16, v178
	v_lshlrev_b32_e32 v243, 16, v179
	v_and_b32_e32 v174, 0xffff0000, v174
	v_and_b32_e32 v175, 0xffff0000, v175
	v_and_b32_e32 v176, 0xffff0000, v176
	v_and_b32_e32 v177, 0xffff0000, v177
	v_and_b32_e32 v178, 0xffff0000, v178
	v_and_b32_e32 v179, 0xffff0000, v179
	v_pk_mul_f32 v[240:241], v[240:241], s[30:31]
	v_pk_mul_f32 v[176:177], v[176:177], s[30:31]
	v_pk_mul_f32 v[242:243], v[242:243], s[30:31]
	v_pk_mul_f32 v[178:179], v[178:179], s[30:31]
	v_exp_f32_e32 v240, v240
	v_exp_f32_e32 v241, v241
	v_exp_f32_e32 v176, v176
	v_exp_f32_e32 v177, v177
	v_exp_f32_e32 v242, v242
	v_exp_f32_e32 v243, v243
	v_exp_f32_e32 v178, v178
	v_exp_f32_e32 v179, v179
	v_pk_add_f32 v[240:241], v[240:241], s[34:35]
	v_pk_add_f32 v[176:177], v[176:177], s[34:35]
	v_pk_add_f32 v[242:243], v[242:243], s[34:35]
	v_pk_add_f32 v[178:179], v[178:179], s[34:35]
	v_rcp_f32_e32 v240, v240
	v_rcp_f32_e32 v241, v241
	v_rcp_f32_e32 v176, v176
	v_rcp_f32_e32 v177, v177
	v_rcp_f32_e32 v242, v242
	v_rcp_f32_e32 v243, v243
	v_rcp_f32_e32 v178, v178
	v_rcp_f32_e32 v179, v179
	v_pk_mul_f32 v[238:239], v[240:241], v[238:239]
	v_pk_mul_f32 v[174:175], v[176:177], v[174:175]
	v_pk_fma_f32 v[238:239], v[242:243], v[64:65], v[238:239]
	v_pk_fma_f32 v[174:175], v[178:179], v[68:69], v[174:175]
	v_cvt_pk_bf16_f32 v240, v238, v174
	v_cvt_pk_bf16_f32 v241, v239, v175
	s_add_u32 s2, s64, 0x61000
	s_addc_u32 s3, s65, 0
	global_store_dword v137, v240, s[2:3] offset:-4096 nt
	s_add_u32 s2, s64, 0x63000
	s_addc_u32 s3, s65, 0
	global_store_dword v137, v241, s[2:3] offset:-4096 nt
	s_waitcnt vmcnt(62)
; __device__ __forceinline__ float sigm(float x) { return __builtin_amdgcn_rcpf(1.f + __expf(-x)); }
; __device__ __forceinline__ void gemm_glu_merge(u16* __restrict__ proj, const u16* __restrict__ Wt) {
;     ...
;           const int row = ai * 128 + wr * 64 + m * 16 + fq * 4 + j;
;           u16* pr = proj + (size_t)row * 4096 + nt * 128 + wc * 32 + fr * 2;
;           const float s0 = acc[ai][0][m][0][j] * sigm(acc[ai][0][m][1][j]);
;           const float s1 = acc[ai][1][m][0][j] * sigm(acc[ai][1][m][1][j]);
;           const unsigned at = *(const unsigned*)pr, ga = *(const unsigned*)(pr + 2048), gs = *(const unsigned*)(pr + 3072);
;           const float m0 = sigm(__uint_as_float(ga << 16)) * __uint_as_float(at << 16) + sigm(__uint_as_float(gs << 16)) * s0;
;           const float m1 = sigm(__uint_as_float(ga & 0xffff0000u)) * __uint_as_float(at & 0xffff0000u) +
;                            sigm(__uint_as_float(gs & 0xffff0000u)) * s1;
;           __builtin_nontemporal_store(pack2(m0, m1), (unsigned*)pr);
	v_lshlrev_b32_e32 v248, 16, v180
	v_lshlrev_b32_e32 v249, 16, v181
	v_lshlrev_b32_e32 v250, 16, v182
	v_lshlrev_b32_e32 v251, 16, v183
	v_lshlrev_b32_e32 v252, 16, v184
	v_lshlrev_b32_e32 v253, 16, v185
	v_and_b32_e32 v180, 0xffff0000, v180
	v_and_b32_e32 v181, 0xffff0000, v181
	v_and_b32_e32 v182, 0xffff0000, v182
	v_and_b32_e32 v183, 0xffff0000, v183
	v_and_b32_e32 v184, 0xffff0000, v184
	v_and_b32_e32 v185, 0xffff0000, v185
	v_pk_mul_f32 v[250:251], v[250:251], s[30:31]
	v_pk_mul_f32 v[182:183], v[182:183], s[30:31]
	v_pk_mul_f32 v[252:253], v[252:253], s[30:31]
	v_pk_mul_f32 v[184:185], v[184:185], s[30:31]
	v_exp_f32_e32 v250, v250
	v_exp_f32_e32 v251, v251
	v_exp_f32_e32 v182, v182
	v_exp_f32_e32 v183, v183
	v_exp_f32_e32 v252, v252
	v_exp_f32_e32 v253, v253
	v_exp_f32_e32 v184, v184
	v_exp_f32_e32 v185, v185
	v_pk_add_f32 v[250:251], v[250:251], s[34:35]
	v_pk_add_f32 v[182:183], v[182:183], s[34:35]
	v_pk_add_f32 v[252:253], v[252:253], s[34:35]
	v_pk_add_f32 v[184:185], v[184:185], s[34:35]
	v_rcp_f32_e32 v250, v250
	v_rcp_f32_e32 v251, v251
	v_rcp_f32_e32 v182, v182
	v_rcp_f32_e32 v183, v183
	v_rcp_f32_e32 v252, v252
	v_rcp_f32_e32 v253, v253
	v_rcp_f32_e32 v184, v184
	v_rcp_f32_e32 v185, v185
	v_pk_mul_f32 v[248:249], v[250:251], v[248:249]
	v_pk_mul_f32 v[180:181], v[182:183], v[180:181]
	v_pk_fma_f32 v[248:249], v[252:253], v[66:67], v[248:249]
	v_pk_fma_f32 v[180:181], v[184:185], v[70:71], v[180:181]
	v_cvt_pk_bf16_f32 v250, v248, v180
	v_cvt_pk_bf16_f32 v251, v249, v181
	s_add_u32 s2, s64, 0x65000
	s_addc_u32 s3, s65, 0
	global_store_dword v137, v250, s[2:3] offset:-4096 nt
	s_add_u32 s2, s64, 0x67000
	s_addc_u32 s3, s65, 0
	global_store_dword v137, v251, s[2:3] offset:-4096 nt
	s_waitcnt vmcnt(58)
	v_lshlrev_b32_e32 v238, 16, v186
	v_lshlrev_b32_e32 v239, 16, v187
	v_lshlrev_b32_e32 v240, 16, v188
	v_lshlrev_b32_e32 v241, 16, v189
	v_lshlrev_b32_e32 v242, 16, v190
	v_lshlrev_b32_e32 v243, 16, v191
	v_and_b32_e32 v186, 0xffff0000, v186
	v_and_b32_e32 v187, 0xffff0000, v187
	v_and_b32_e32 v188, 0xffff0000, v188
	v_and_b32_e32 v189, 0xffff0000, v189
	v_and_b32_e32 v190, 0xffff0000, v190
	v_and_b32_e32 v191, 0xffff0000, v191
	v_pk_mul_f32 v[240:241], v[240:241], s[30:31]
	v_pk_mul_f32 v[188:189], v[188:189], s[30:31]
	v_pk_mul_f32 v[242:243], v[242:243], s[30:31]
	v_pk_mul_f32 v[190:191], v[190:191], s[30:31]
	v_exp_f32_e32 v240, v240
	v_exp_f32_e32 v241, v241
	v_exp_f32_e32 v188, v188
	v_exp_f32_e32 v189, v189
	v_exp_f32_e32 v242, v242
	v_exp_f32_e32 v243, v243
	v_exp_f32_e32 v190, v190
	v_exp_f32_e32 v191, v191
	v_pk_add_f32 v[240:241], v[240:241], s[34:35]
	v_pk_add_f32 v[188:189], v[188:189], s[34:35]
	v_pk_add_f32 v[242:243], v[242:243], s[34:35]
	v_pk_add_f32 v[190:191], v[190:191], s[34:35]
	v_rcp_f32_e32 v240, v240
	v_rcp_f32_e32 v241, v241
	v_rcp_f32_e32 v188, v188
	v_rcp_f32_e32 v189, v189
	v_rcp_f32_e32 v242, v242
	v_rcp_f32_e32 v243, v243
	v_rcp_f32_e32 v190, v190
	v_rcp_f32_e32 v191, v191
	v_pk_mul_f32 v[238:239], v[240:241], v[238:239]
	v_pk_mul_f32 v[186:187], v[188:189], v[186:187]
	v_pk_fma_f32 v[238:239], v[242:243], v[48:49], v[238:239]
	v_pk_fma_f32 v[186:187], v[190:191], v[52:53], v[186:187]
	v_cvt_pk_bf16_f32 v240, v238, v186
	v_cvt_pk_bf16_f32 v241, v239, v187
	s_add_u32 s2, s64, 0x101000
	s_addc_u32 s3, s65, 0
	global_store_dword v137, v240, s[2:3] offset:-4096 nt
	s_add_u32 s2, s64, 0x103000
	s_addc_u32 s3, s65, 0
	global_store_dword v137, v241, s[2:3] offset:-4096 nt
	s_waitcnt vmcnt(54)
	v_lshlrev_b32_e32 v248, 16, v192
	v_lshlrev_b32_e32 v249, 16, v193
	v_lshlrev_b32_e32 v250, 16, v194
	v_lshlrev_b32_e32 v251, 16, v195
	v_lshlrev_b32_e32 v252, 16, v196
	v_lshlrev_b32_e32 v253, 16, v197
	v_and_b32_e32 v192, 0xffff0000, v192
	v_and_b32_e32 v193, 0xffff0000, v193
	v_and_b32_e32 v194, 0xffff0000, v194
	v_and_b32_e32 v195, 0xffff0000, v195
	v_and_b32_e32 v196, 0xffff0000, v196
	v_and_b32_e32 v197, 0xffff0000, v197
	v_pk_mul_f32 v[250:251], v[250:251], s[30:31]
	v_pk_mul_f32 v[194:195], v[194:195], s[30:31]
	v_pk_mul_f32 v[252:253], v[252:253], s[30:31]
	v_pk_mul_f32 v[196:197], v[196:197], s[30:31]
	v_exp_f32_e32 v250, v250
	v_exp_f32_e32 v251, v251
	v_exp_f32_e32 v194, v194
	v_exp_f32_e32 v195, v195
	v_exp_f32_e32 v252, v252
	v_exp_f32_e32 v253, v253
	v_exp_f32_e32 v196, v196
	v_exp_f32_e32 v197, v197
	v_pk_add_f32 v[250:251], v[250:251], s[34:35]
	v_pk_add_f32 v[194:195], v[194:195], s[34:35]
	v_pk_add_f32 v[252:253], v[252:253], s[34:35]
	v_pk_add_f32 v[196:197], v[196:197], s[34:35]
	v_rcp_f32_e32 v250, v250
	v_rcp_f32_e32 v251, v251
	v_rcp_f32_e32 v194, v194
	v_rcp_f32_e32 v195, v195
	v_rcp_f32_e32 v252, v252
	v_rcp_f32_e32 v253, v253
	v_rcp_f32_e32 v196, v196
	v_rcp_f32_e32 v197, v197
	v_pk_mul_f32 v[248:249], v[250:251], v[248:249]
	v_pk_mul_f32 v[192:193], v[194:195], v[192:193]
	v_pk_fma_f32 v[248:249], v[252:253], v[50:51], v[248:249]
	v_pk_fma_f32 v[192:193], v[196:197], v[54:55], v[192:193]
	v_cvt_pk_bf16_f32 v250, v248, v192
	v_cvt_pk_bf16_f32 v251, v249, v193
	s_add_u32 s2, s64, 0x105000
	s_addc_u32 s3, s65, 0
	global_store_dword v137, v250, s[2:3] offset:-4096 nt
	s_add_u32 s2, s64, 0x107000
	s_addc_u32 s3, s65, 0
	global_store_dword v137, v251, s[2:3] offset:-4096 nt
	s_waitcnt vmcnt(50)
; __device__ __forceinline__ float sigm(float x) { return __builtin_amdgcn_rcpf(1.f + __expf(-x)); }
; __device__ __forceinline__ void gemm_glu_merge(u16* __restrict__ proj, const u16* __restrict__ Wt) {
;     ...
;           const int row = ai * 128 + wr * 64 + m * 16 + fq * 4 + j;
;           u16* pr = proj + (size_t)row * 4096 + nt * 128 + wc * 32 + fr * 2;
;           const float s0 = acc[ai][0][m][0][j] * sigm(acc[ai][0][m][1][j]);
;           const float s1 = acc[ai][1][m][0][j] * sigm(acc[ai][1][m][1][j]);
;           const unsigned at = *(const unsigned*)pr, ga = *(const unsigned*)(pr + 2048), gs = *(const unsigned*)(pr + 3072);
;           const float m0 = sigm(__uint_as_float(ga << 16)) * __uint_as_float(at << 16) + sigm(__uint_as_float(gs << 16)) * s0;
;           const float m1 = sigm(__uint_as_float(ga & 0xffff0000u)) * __uint_as_float(at & 0xffff0000u) +
;                            sigm(__uint_as_float(gs & 0xffff0000u)) * s1;
;           __builtin_nontemporal_store(pack2(m0, m1), (unsigned*)pr);
	v_lshlrev_b32_e32 v238, 16, v198
	v_lshlrev_b32_e32 v239, 16, v199
	v_lshlrev_b32_e32 v240, 16, v200
	v_lshlrev_b32_e32 v241, 16, v201
	v_lshlrev_b32_e32 v242, 16, v202
	v_lshlrev_b32_e32 v243, 16, v203
	v_and_b32_e32 v198, 0xffff0000, v198
	v_and_b32_e32 v199, 0xffff0000, v199
	v_and_b32_e32 v200, 0xffff0000, v200
	v_and_b32_e32 v201, 0xffff0000, v201
	v_and_b32_e32 v202, 0xffff0000, v202
	v_and_b32_e32 v203, 0xffff0000, v203
	v_pk_mul_f32 v[240:241], v[240:241], s[30:31]
	v_pk_mul_f32 v[200:201], v[200:201], s[30:31]
	v_pk_mul_f32 v[242:243], v[242:243], s[30:31]
	v_pk_mul_f32 v[202:203], v[202:203], s[30:31]
	v_exp_f32_e32 v240, v240
	v_exp_f32_e32 v241, v241
	v_exp_f32_e32 v200, v200
	v_exp_f32_e32 v201, v201
	v_exp_f32_e32 v242, v242
	v_exp_f32_e32 v243, v243
	v_exp_f32_e32 v202, v202
	v_exp_f32_e32 v203, v203
	v_pk_add_f32 v[240:241], v[240:241], s[34:35]
	v_pk_add_f32 v[200:201], v[200:201], s[34:35]
	v_pk_add_f32 v[242:243], v[242:243], s[34:35]
	v_pk_add_f32 v[202:203], v[202:203], s[34:35]
	v_rcp_f32_e32 v240, v240
	v_rcp_f32_e32 v241, v241
	v_rcp_f32_e32 v200, v200
	v_rcp_f32_e32 v201, v201
	v_rcp_f32_e32 v242, v242
	v_rcp_f32_e32 v243, v243
	v_rcp_f32_e32 v202, v202
	v_rcp_f32_e32 v203, v203
	v_pk_mul_f32 v[238:239], v[240:241], v[238:239]
	v_pk_mul_f32 v[198:199], v[200:201], v[198:199]
	v_pk_fma_f32 v[238:239], v[242:243], v[32:33], v[238:239]
	v_pk_fma_f32 v[198:199], v[202:203], v[36:37], v[198:199]
	v_cvt_pk_bf16_f32 v240, v238, v198
	v_cvt_pk_bf16_f32 v241, v239, v199
	s_add_u32 s2, s64, 0x121000
	s_addc_u32 s3, s65, 0
	global_store_dword v137, v240, s[2:3] offset:-4096 nt
	s_add_u32 s2, s64, 0x123000
	s_addc_u32 s3, s65, 0
	global_store_dword v137, v241, s[2:3] offset:-4096 nt
	s_waitcnt vmcnt(46)
	v_lshlrev_b32_e32 v248, 16, v204
	v_lshlrev_b32_e32 v249, 16, v205
	v_lshlrev_b32_e32 v250, 16, v206
	v_lshlrev_b32_e32 v251, 16, v207
	v_lshlrev_b32_e32 v252, 16, v208
	v_lshlrev_b32_e32 v253, 16, v209
	v_and_b32_e32 v204, 0xffff0000, v204
	v_and_b32_e32 v205, 0xffff0000, v205
	v_and_b32_e32 v206, 0xffff0000, v206
	v_and_b32_e32 v207, 0xffff0000, v207
	v_and_b32_e32 v208, 0xffff0000, v208
	v_and_b32_e32 v209, 0xffff0000, v209
	v_pk_mul_f32 v[250:251], v[250:251], s[30:31]
	v_pk_mul_f32 v[206:207], v[206:207], s[30:31]
	v_pk_mul_f32 v[252:253], v[252:253], s[30:31]
	v_pk_mul_f32 v[208:209], v[208:209], s[30:31]
	v_exp_f32_e32 v250, v250
	v_exp_f32_e32 v251, v251
	v_exp_f32_e32 v206, v206
	v_exp_f32_e32 v207, v207
	v_exp_f32_e32 v252, v252
	v_exp_f32_e32 v253, v253
	v_exp_f32_e32 v208, v208
	v_exp_f32_e32 v209, v209
	v_pk_add_f32 v[250:251], v[250:251], s[34:35]
	v_pk_add_f32 v[206:207], v[206:207], s[34:35]
	v_pk_add_f32 v[252:253], v[252:253], s[34:35]
	v_pk_add_f32 v[208:209], v[208:209], s[34:35]
	v_rcp_f32_e32 v250, v250
	v_rcp_f32_e32 v251, v251
	v_rcp_f32_e32 v206, v206
	v_rcp_f32_e32 v207, v207
	v_rcp_f32_e32 v252, v252
	v_rcp_f32_e32 v253, v253
	v_rcp_f32_e32 v208, v208
	v_rcp_f32_e32 v209, v209
	v_pk_mul_f32 v[248:249], v[250:251], v[248:249]
	v_pk_mul_f32 v[204:205], v[206:207], v[204:205]
	v_pk_fma_f32 v[248:249], v[252:253], v[34:35], v[248:249]
	v_pk_fma_f32 v[204:205], v[208:209], v[38:39], v[204:205]
	v_cvt_pk_bf16_f32 v250, v248, v204
	v_cvt_pk_bf16_f32 v251, v249, v205
	s_add_u32 s2, s64, 0x125000
	s_addc_u32 s3, s65, 0
	global_store_dword v137, v250, s[2:3] offset:-4096 nt
	s_add_u32 s2, s64, 0x127000
	s_addc_u32 s3, s65, 0
	global_store_dword v137, v251, s[2:3] offset:-4096 nt
	s_waitcnt vmcnt(42)
	v_lshlrev_b32_e32 v238, 16, v210
	v_lshlrev_b32_e32 v239, 16, v211
	v_lshlrev_b32_e32 v240, 16, v212
	v_lshlrev_b32_e32 v241, 16, v213
	v_lshlrev_b32_e32 v242, 16, v214
	v_lshlrev_b32_e32 v243, 16, v215
	v_and_b32_e32 v210, 0xffff0000, v210
	v_and_b32_e32 v211, 0xffff0000, v211
	v_and_b32_e32 v212, 0xffff0000, v212
	v_and_b32_e32 v213, 0xffff0000, v213
	v_and_b32_e32 v214, 0xffff0000, v214
	v_and_b32_e32 v215, 0xffff0000, v215
	v_pk_mul_f32 v[240:241], v[240:241], s[30:31]
	v_pk_mul_f32 v[212:213], v[212:213], s[30:31]
	v_pk_mul_f32 v[242:243], v[242:243], s[30:31]
	v_pk_mul_f32 v[214:215], v[214:215], s[30:31]
	v_exp_f32_e32 v240, v240
	v_exp_f32_e32 v241, v241
	v_exp_f32_e32 v212, v212
	v_exp_f32_e32 v213, v213
	v_exp_f32_e32 v242, v242
	v_exp_f32_e32 v243, v243
	v_exp_f32_e32 v214, v214
	v_exp_f32_e32 v215, v215
	v_pk_add_f32 v[240:241], v[240:241], s[34:35]
	v_pk_add_f32 v[212:213], v[212:213], s[34:35]
	v_pk_add_f32 v[242:243], v[242:243], s[34:35]
	v_pk_add_f32 v[214:215], v[214:215], s[34:35]
	v_rcp_f32_e32 v240, v240
	v_rcp_f32_e32 v241, v241
	v_rcp_f32_e32 v212, v212
	v_rcp_f32_e32 v213, v213
	v_rcp_f32_e32 v242, v242
	v_rcp_f32_e32 v243, v243
	v_rcp_f32_e32 v214, v214
	v_rcp_f32_e32 v215, v215
	v_pk_mul_f32 v[238:239], v[240:241], v[238:239]
	v_pk_mul_f32 v[210:211], v[212:213], v[210:211]
	v_pk_fma_f32 v[238:239], v[242:243], v[16:17], v[238:239]
	v_pk_fma_f32 v[210:211], v[214:215], v[20:21], v[210:211]
	v_cvt_pk_bf16_f32 v240, v238, v210
	v_cvt_pk_bf16_f32 v241, v239, v211
	s_add_u32 s2, s64, 0x141000
	s_addc_u32 s3, s65, 0
	global_store_dword v137, v240, s[2:3] offset:-4096 nt
	s_add_u32 s2, s64, 0x143000
	s_addc_u32 s3, s65, 0
	global_store_dword v137, v241, s[2:3] offset:-4096 nt
	s_waitcnt vmcnt(38)
; __device__ __forceinline__ float sigm(float x) { return __builtin_amdgcn_rcpf(1.f + __expf(-x)); }
; __device__ __forceinline__ void gemm_glu_merge(u16* __restrict__ proj, const u16* __restrict__ Wt) {
;     ...
;           const float s0 = acc[ai][0][m][0][j] * sigm(acc[ai][0][m][1][j]);
;           const float s1 = acc[ai][1][m][0][j] * sigm(acc[ai][1][m][1][j]);
;           const unsigned at = *(const unsigned*)pr, ga = *(const unsigned*)(pr + 2048), gs = *(const unsigned*)(pr + 3072);
;           const float m0 = sigm(__uint_as_float(ga << 16)) * __uint_as_float(at << 16) + sigm(__uint_as_float(gs << 16)) * s0;
;           const float m1 = sigm(__uint_as_float(ga & 0xffff0000u)) * __uint_as_float(at & 0xffff0000u) +
;                            sigm(__uint_as_float(gs & 0xffff0000u)) * s1;
;           __builtin_nontemporal_store(pack2(m0, m1), (unsigned*)pr);
	v_lshlrev_b32_e32 v248, 16, v216
	v_lshlrev_b32_e32 v249, 16, v217
	v_lshlrev_b32_e32 v250, 16, v218
	v_lshlrev_b32_e32 v251, 16, v219
	v_lshlrev_b32_e32 v252, 16, v220
	v_lshlrev_b32_e32 v253, 16, v221
	v_and_b32_e32 v216, 0xffff0000, v216
	v_and_b32_e32 v217, 0xffff0000, v217
	v_and_b32_e32 v218, 0xffff0000, v218
	v_and_b32_e32 v219, 0xffff0000, v219
	v_and_b32_e32 v220, 0xffff0000, v220
	v_and_b32_e32 v221, 0xffff0000, v221
	v_pk_mul_f32 v[250:251], v[250:251], s[30:31]
	v_pk_mul_f32 v[218:219], v[218:219], s[30:31]
	v_pk_mul_f32 v[252:253], v[252:253], s[30:31]
	v_pk_mul_f32 v[220:221], v[220:221], s[30:31]
	v_exp_f32_e32 v250, v250
	v_exp_f32_e32 v251, v251
	v_exp_f32_e32 v218, v218
	v_exp_f32_e32 v219, v219
	v_exp_f32_e32 v252, v252
	v_exp_f32_e32 v253, v253
	v_exp_f32_e32 v220, v220
	v_exp_f32_e32 v221, v221
	v_pk_add_f32 v[250:251], v[250:251], s[34:35]
	v_pk_add_f32 v[218:219], v[218:219], s[34:35]
	v_pk_add_f32 v[252:253], v[252:253], s[34:35]
	v_pk_add_f32 v[220:221], v[220:221], s[34:35]
	v_rcp_f32_e32 v250, v250
	v_rcp_f32_e32 v251, v251
	v_rcp_f32_e32 v218, v218
	v_rcp_f32_e32 v219, v219
	v_rcp_f32_e32 v252, v252
	v_rcp_f32_e32 v253, v253
	v_rcp_f32_e32 v220, v220
	v_rcp_f32_e32 v221, v221
	v_pk_mul_f32 v[248:249], v[250:251], v[248:249]
	v_pk_mul_f32 v[216:217], v[218:219], v[216:217]
	v_pk_fma_f32 v[248:249], v[252:253], v[18:19], v[248:249]
	v_pk_fma_f32 v[216:217], v[220:221], v[22:23], v[216:217]
	v_cvt_pk_bf16_f32 v250, v248, v216
	v_cvt_pk_bf16_f32 v251, v249, v217
	s_add_u32 s2, s64, 0x145000
	s_addc_u32 s3, s65, 0
	global_store_dword v137, v250, s[2:3] offset:-4096 nt
	s_add_u32 s2, s64, 0x147000
	s_addc_u32 s3, s65, 0
	global_store_dword v137, v251, s[2:3] offset:-4096 nt
	s_waitcnt vmcnt(34)
	v_lshlrev_b32_e32 v238, 16, v222
	v_lshlrev_b32_e32 v239, 16, v223
	v_lshlrev_b32_e32 v240, 16, v224
	v_lshlrev_b32_e32 v241, 16, v225
	v_lshlrev_b32_e32 v242, 16, v226
	v_lshlrev_b32_e32 v243, 16, v227
	v_and_b32_e32 v222, 0xffff0000, v222
	v_and_b32_e32 v223, 0xffff0000, v223
	v_and_b32_e32 v224, 0xffff0000, v224
	v_and_b32_e32 v225, 0xffff0000, v225
	v_and_b32_e32 v226, 0xffff0000, v226
	v_and_b32_e32 v227, 0xffff0000, v227
	v_pk_mul_f32 v[240:241], v[240:241], s[30:31]
	v_pk_mul_f32 v[224:225], v[224:225], s[30:31]
	v_pk_mul_f32 v[242:243], v[242:243], s[30:31]
	v_pk_mul_f32 v[226:227], v[226:227], s[30:31]
	v_exp_f32_e32 v240, v240
	v_exp_f32_e32 v241, v241
	v_exp_f32_e32 v224, v224
	v_exp_f32_e32 v225, v225
	v_exp_f32_e32 v242, v242
	v_exp_f32_e32 v243, v243
	v_exp_f32_e32 v226, v226
	v_exp_f32_e32 v227, v227
	v_pk_add_f32 v[240:241], v[240:241], s[34:35]
	v_pk_add_f32 v[224:225], v[224:225], s[34:35]
	v_pk_add_f32 v[242:243], v[242:243], s[34:35]
	v_pk_add_f32 v[226:227], v[226:227], s[34:35]
	v_rcp_f32_e32 v240, v240
	v_rcp_f32_e32 v241, v241
	v_rcp_f32_e32 v224, v224
	v_rcp_f32_e32 v225, v225
	v_rcp_f32_e32 v242, v242
	v_rcp_f32_e32 v243, v243
	v_rcp_f32_e32 v226, v226
	v_rcp_f32_e32 v227, v227
	v_pk_mul_f32 v[238:239], v[240:241], v[238:239]
	v_pk_mul_f32 v[222:223], v[224:225], v[222:223]
	v_pk_fma_f32 v[238:239], v[242:243], v[0:1], v[238:239]
	v_pk_fma_f32 v[222:223], v[226:227], v[4:5], v[222:223]
	v_cvt_pk_bf16_f32 v240, v238, v222
	v_cvt_pk_bf16_f32 v241, v239, v223
	s_add_u32 s2, s64, 0x161000
	s_addc_u32 s3, s65, 0
	global_store_dword v137, v240, s[2:3] offset:-4096 nt
	s_add_u32 s2, s64, 0x163000
	s_addc_u32 s3, s65, 0
	global_store_dword v137, v241, s[2:3] offset:-4096 nt
	s_waitcnt vmcnt(30)
	v_lshlrev_b32_e32 v248, 16, v228
	v_lshlrev_b32_e32 v249, 16, v229
	v_lshlrev_b32_e32 v250, 16, v230
	v_lshlrev_b32_e32 v251, 16, v231
	v_lshlrev_b32_e32 v252, 16, v232
	v_lshlrev_b32_e32 v253, 16, v233
	v_and_b32_e32 v228, 0xffff0000, v228
	v_and_b32_e32 v229, 0xffff0000, v229
	v_and_b32_e32 v230, 0xffff0000, v230
	v_and_b32_e32 v231, 0xffff0000, v231
	v_and_b32_e32 v232, 0xffff0000, v232
	v_and_b32_e32 v233, 0xffff0000, v233
	v_pk_mul_f32 v[250:251], v[250:251], s[30:31]
	v_pk_mul_f32 v[230:231], v[230:231], s[30:31]
	v_pk_mul_f32 v[252:253], v[252:253], s[30:31]
	v_pk_mul_f32 v[232:233], v[232:233], s[30:31]
	v_exp_f32_e32 v250, v250
	v_exp_f32_e32 v251, v251
	v_exp_f32_e32 v230, v230
	v_exp_f32_e32 v231, v231
	v_exp_f32_e32 v252, v252
	v_exp_f32_e32 v253, v253
	v_exp_f32_e32 v232, v232
	v_exp_f32_e32 v233, v233
	v_pk_add_f32 v[250:251], v[250:251], s[34:35]
	v_pk_add_f32 v[230:231], v[230:231], s[34:35]
	v_pk_add_f32 v[252:253], v[252:253], s[34:35]
	v_pk_add_f32 v[232:233], v[232:233], s[34:35]
	v_rcp_f32_e32 v250, v250
	v_rcp_f32_e32 v251, v251
	v_rcp_f32_e32 v230, v230
	v_rcp_f32_e32 v231, v231
	v_rcp_f32_e32 v252, v252
	v_rcp_f32_e32 v253, v253
	v_rcp_f32_e32 v232, v232
	v_rcp_f32_e32 v233, v233
	v_pk_mul_f32 v[248:249], v[250:251], v[248:249]
	v_pk_mul_f32 v[228:229], v[230:231], v[228:229]
	v_pk_fma_f32 v[248:249], v[252:253], v[2:3], v[248:249]
	v_pk_fma_f32 v[228:229], v[232:233], v[6:7], v[228:229]
	v_cvt_pk_bf16_f32 v250, v248, v228
	v_cvt_pk_bf16_f32 v251, v249, v229
	s_add_u32 s2, s64, 0x165000
	s_addc_u32 s3, s65, 0
	global_store_dword v137, v250, s[2:3] offset:-4096 nt
	s_add_u32 s2, s64, 0x167000
	s_addc_u32 s3, s65, 0
	global_store_dword v137, v251, s[2:3] offset:-4096 nt
	s_mov_b32 s30, 0x80100
	s_mov_b32 s31, 0x20100
	s_mov_b32 s34, 0x30100
	s_mov_b32 s35, 0x100100
	s_add_i32 s12, s12, 1
	s_cmp_lg_u32 s12, 8
	s_cbranch_scc0 .LBB0_367
; __device__ __forceinline__ int opaque_tid() { int t = threadIdx.x; asm volatile("" : "+v"(t)); return t; }
; #define WAIT_V(n) asm volatile("s_waitcnt vmcnt(" #n ")" ::: "memory")
; #define BAR __builtin_amdgcn_s_barrier()
; template <bool PEEL = false>
; __device__ __forceinline__ void gemm_tile(f32x4 (&acc)[2][2][4][2], const u16* __restrict__ A, int lda,
;                                           const u16* __restrict__ B, int K) {
;     ...
;   const int tid = opaque_tid();
;   const int wid = tid >> 6, lane = tid & 63, wr = wid >> 2, wc = wid & 3, fr = lane & 15, fq = lane >> 4;
;   int rA0, rB0;
;   {
;     int r, c;
;     stage_rc(tid * 16, r, c);
;     rA0 = (r * lda + c) * 2; rB0 = (r * K + c) * 2;
;   }
;   const int wbase = __builtin_amdgcn_readfirstlane(wid) * 1024;
;   const __amdgpu_buffer_rsrc_t rsA = __builtin_amdgcn_make_buffer_rsrc((void*)A, 0, 0x40000000, 0x00020000);
;   const __amdgpu_buffer_rsrc_t rsB = __builtin_amdgcn_make_buffer_rsrc((void*)B, 0, 0x40000000, 0x00020000);
; #pragma unroll
;   for (int a = 0; a < 2; ++a)
; #pragma unroll
;     for (int b = 0; b < 2; ++b)
; #pragma unroll
;       for (int m = 0; m < 4; ++m)
; #pragma unroll
;         for (int n = 0; n < 2; ++n) acc[a][b][m][n] = f32x4{0.f, 0.f, 0.f, 0.f};
;   bf16x8 At[4][2], B0[2][2], B1[2][2];
;   const int nt = K / 64;
;   STAGE_B(SB(0, 0), 0, 0); STAGE_A(SA(0, 0), 0, 0);
;   STAGE_B(SB(0, 1), 1, 0); STAGE_A(SA(0, 1), 1, 0);
;   if (wr == 1) BAR;
;   WAIT_V(4); BAR;
;   STAGE_B(SB(1, 0), 0, 1); STAGE_A(SA(1, 0), 0, 1); STAGE_B(SB(1, 1), 1, 1);
;   WAIT_V(6); BAR;
.LBB0_361:
	v_mov_b32_e32 v129, v254
	s_lshl_b32 s2, s12, 18
	v_bfe_i32 v3, v129, 27, 1
	v_lshlrev_b32_e32 v1, 4, v129
	v_lshrrev_b32_e32 v3, 22, v3
	v_add_u32_e32 v3, v1, v3
	v_and_b32_e32 v3, 0xfffffc00, v3
	v_ashrrev_i32_e32 v2, 31, v129
	v_sub_u32_e32 v1, v1, v3
	v_lshrrev_b32_e32 v2, 26, v2
	v_lshrrev_b32_e32 v3, 4, v1
	v_add_u32_e32 v2, v129, v2
	v_bitop3_b32 v3, v3, v1, 32 bitop3:0x6c
	v_ashrrev_i32_e32 v1, 31, v1
	v_ashrrev_i32_e32 v2, 6, v2
	v_lshrrev_b32_e32 v1, 26, v1
	v_lshlrev_b32_e32 v4, 3, v2
	v_add_u32_e32 v1, v3, v1
	v_and_b32_e32 v4, -16, v4
	v_ashrrev_i32_e32 v1, 6, v1
	v_ashrrev_i32_e32 v0, 6, v129
	v_add_u32_e32 v4, v1, v4
	v_mul_i32_i24_e32 v1, 64, v1
	s_add_u32 s8, s0, s2
	v_lshlrev_b32_e32 v2, 5, v2
	v_sub_u32_e32 v1, v3, v1
	v_readfirstlane_b32 s10, v0
	s_addc_u32 s9, s1, 0
	v_and_b32_e32 v2, 32, v2
	v_ashrrev_i16_sdwa v1, v136, sext(v1) dst_sel:DWORD dst_unused:UNUSED_PAD src0_sel:DWORD src1_sel:BYTE_0
	s_lshl_b32 s78, s10, 10
	v_add_u32_sdwa v1, v2, sext(v1) dst_sel:DWORD dst_unused:UNUSED_PAD src0_sel:DWORD src1_sel:WORD_0
	v_lshlrev_b32_e32 v2, 13, v4
	s_add_i32 s44, s78, 0
	v_lshl_add_u32 v128, v1, 1, v2
	s_add_i32 s45, s44, 0x10000
	v_mad_u64_u32 v[130:131], s[2:3], v4, s13, v[128:129]
	s_and_b32 s9, s9, 0xffff
	s_mov_b32 s10, s6
	s_mov_b32 s11, s7
	s_add_i32 s46, s44, 0x12000
	s_add_i32 s47, s44, 0x2000
	s_add_i32 s48, s44, 0x14000
	s_add_i32 s49, s44, 0x16000
	s_add_i32 s52, s44, 0x4000
	s_add_i32 s53, s44, 0x6000
	s_add_i32 s66, s44, 0x8000
	s_add_i32 s67, s44, 0xa000
	s_add_i32 s78, s68, s44
	s_add_i32 s79, s78, 0x2000
	v_ashrrev_i32_e32 v1, 8, v129
	v_cmp_eq_u32_e32 vcc, 1, v1
	s_cmp_lg_u32 s12, 0
	s_cbranch_scc1 .Lpf4_hdr
	s_mov_b32 m0, s45
	s_nop 0
	buffer_load_dwordx4 v130, s[8:11], 0 offen lds
	s_mov_b32 m0, s46
	s_nop 0
	buffer_load_dwordx4 v130, s[8:11], s14 offen lds
	s_mov_b32 m0, s44
	s_nop 0
	buffer_load_dwordx4 v128, s[4:7], 0 offen lds
	s_mov_b32 m0, s47
	s_nop 0
	buffer_load_dwordx4 v128, s[4:7], s15 offen lds
	s_mov_b32 m0, s48
	s_nop 0
	buffer_load_dwordx4 v130, s[8:11], s7 offen lds
	s_mov_b32 m0, s49
	s_nop 0
	buffer_load_dwordx4 v130, s[8:11], s16 offen lds
	s_mov_b32 m0, s52
	s_nop 0
	buffer_load_dwordx4 v128, s[4:7], s17 offen lds
	s_mov_b32 m0, s53
	s_nop 0
	buffer_load_dwordx4 v128, s[4:7], s18 offen lds
	s_and_saveexec_b64 s[2:3], vcc
	s_cbranch_execz .Lpf4_b0
	s_barrier
.Lpf4_b0:
	s_or_b64 exec, exec, s[2:3]
	s_waitcnt vmcnt(4)
	s_barrier
	s_add_i32 m0, s44, 0x18000
	s_nop 0
	buffer_load_dwordx4 v130, s[8:11], s19 offen lds
	s_add_i32 m0, s44, 0x1a000
	s_nop 0
	buffer_load_dwordx4 v130, s[8:11], s20 offen lds
	s_mov_b32 m0, s66
	s_nop 0
	buffer_load_dwordx4 v128, s[4:7], s19 offen lds
	s_mov_b32 m0, s67
	s_nop 0
	buffer_load_dwordx4 v128, s[4:7], s21 offen lds
	s_mov_b32 m0, s78
	s_nop 0
	buffer_load_dwordx4 v130, s[8:11], s22 offen lds
	s_mov_b32 m0, s79
	s_nop 0
	buffer_load_dwordx4 v130, s[8:11], s23 offen lds
	s_waitcnt vmcnt(6)
	s_branch .Lpf4_join

.Lpf4_join:
	s_add_i32 s2, s97, s44
	s_add_i32 s3, s2, 0x2000
	v_and_b32_e32 v2, 15, v129
	v_lshlrev_b32_e32 v0, 12, v0
	v_and_b32_e32 v126, 0x3000, v0
	v_lshlrev_b32_e32 v0, 6, v2
	v_lshlrev_b32_e32 v2, 2, v129
	v_and_b32_e32 v26, 48, v129
	v_and_b32_e32 v27, 32, v2
	v_bitop3_b32 v127, v0, v27, v26 bitop3:0x36
	v_add_u32_e32 v0, s69, v127
	v_add_u32_e32 v140, v0, v126
	s_barrier
	ds_read_b128 v[2:5], v140
	ds_read_b128 v[6:9], v140 offset:1024
	ds_read_b128 v[10:13], v140 offset:2048
	ds_read_b128 v[14:17], v140 offset:3072
	v_lshlrev_b32_e32 v0, 13, v1
	v_add_u32_e32 v1, 0, v127
	v_add_u32_e32 v131, v1, v0
	v_lshlrev_b32_e32 v1, 6, v129
	v_and_or_b32 v1, v1, s24, v26
	v_xad_u32 v1, v1, v27, 0
	v_or_b32_e32 v26, 0x800, v0
	v_or_b32_e32 v34, 0x1000, v0
	v_or_b32_e32 v0, 0x1800, v0
	s_add_i32 s81, s44, 0xc000
	v_add_u32_e32 v137, v1, v26
	v_add_u32_e32 v138, v1, v34
	v_add_u32_e32 v139, v1, v0
	s_mov_b32 m0, s81
	s_add_i32 s82, s44, 0xe000
	ds_read_b128 v[18:21], v131
	ds_read_b128 v[22:25], v131 offset:1024
	ds_read_b128 v[26:29], v137
	ds_read_b128 v[30:33], v137 offset:1024
	ds_read_b128 v[34:37], v138
	ds_read_b128 v[38:41], v138 offset:1024
	ds_read_b128 v[42:45], v139
	ds_read_b128 v[46:49], v139 offset:1024
	buffer_load_dwordx4 v128, s[4:7], s26 offen lds
	s_mov_b32 m0, s82
	s_nop 0
	buffer_load_dwordx4 v128, s[4:7], s27 offen lds
	s_waitcnt lgkmcnt(8)
	s_barrier
	s_waitcnt lgkmcnt(0)
	s_setprio 1
	s_waitcnt lgkmcnt(7)
	v_mfma_f32_16x16x32_bf16 v[50:53], v[18:21], v[2:5], 0
	v_mfma_f32_16x16x32_bf16 v[54:57], v[18:21], v[10:13], 0
	s_waitcnt lgkmcnt(5)
	v_mfma_f32_16x16x32_bf16 v[58:61], v[26:29], v[2:5], 0
	v_mfma_f32_16x16x32_bf16 v[62:65], v[26:29], v[10:13], 0
	s_waitcnt lgkmcnt(3)
	v_mfma_f32_16x16x32_bf16 v[66:69], v[34:37], v[2:5], 0
	v_mfma_f32_16x16x32_bf16 v[70:73], v[34:37], v[10:13], 0
	s_waitcnt lgkmcnt(1)
	v_mfma_f32_16x16x32_bf16 v[74:77], v[42:45], v[2:5], 0
	v_mfma_f32_16x16x32_bf16 v[78:81], v[42:45], v[10:13], 0
	v_mfma_f32_16x16x32_bf16 v[50:53], v[22:25], v[6:9], v[50:53]
	v_mfma_f32_16x16x32_bf16 v[54:57], v[22:25], v[14:17], v[54:57]
	v_mfma_f32_16x16x32_bf16 v[58:61], v[30:33], v[6:9], v[58:61]
	v_mfma_f32_16x16x32_bf16 v[62:65], v[30:33], v[14:17], v[62:65]
	v_mfma_f32_16x16x32_bf16 v[66:69], v[38:41], v[6:9], v[66:69]
	v_mfma_f32_16x16x32_bf16 v[70:73], v[38:41], v[14:17], v[70:73]
	s_waitcnt lgkmcnt(0)
	v_mfma_f32_16x16x32_bf16 v[74:77], v[46:49], v[6:9], v[74:77]
	v_mfma_f32_16x16x32_bf16 v[78:81], v[46:49], v[14:17], v[78:81]
	s_setprio 0
	s_barrier
	v_add_u32_e32 v0, s70, v127
	v_add_u32_e32 v141, v0, v126
	s_mov_b32 m0, s45
	ds_read_b128 v[82:85], v141
	ds_read_b128 v[86:89], v141 offset:1024
	ds_read_b128 v[90:93], v141 offset:2048
	ds_read_b128 v[94:97], v141 offset:3072
	buffer_load_dwordx4 v130, s[8:11], s28 offen lds
	s_mov_b32 m0, s46
	s_nop 0
	buffer_load_dwordx4 v130, s[8:11], s29 offen lds
	s_barrier
	s_waitcnt lgkmcnt(0)
	s_setprio 1
	s_waitcnt lgkmcnt(3)
	v_mfma_f32_16x16x32_bf16 v[98:101], v[18:21], v[82:85], 0
	s_waitcnt lgkmcnt(1)
	v_mfma_f32_16x16x32_bf16 v[18:21], v[18:21], v[90:93], 0
	s_waitcnt lgkmcnt(0)
	v_mfma_f32_16x16x32_bf16 v[102:105], v[22:25], v[94:97], v[18:21]
	v_mfma_f32_16x16x32_bf16 v[18:21], v[26:29], v[82:85], 0
	v_mfma_f32_16x16x32_bf16 v[106:109], v[30:33], v[86:89], v[18:21]
	v_mfma_f32_16x16x32_bf16 v[18:21], v[26:29], v[90:93], 0
	v_mfma_f32_16x16x32_bf16 v[110:113], v[30:33], v[94:97], v[18:21]
	v_mfma_f32_16x16x32_bf16 v[18:21], v[34:37], v[82:85], 0
	v_mfma_f32_16x16x32_bf16 v[114:117], v[38:41], v[86:89], v[18:21]
	v_mfma_f32_16x16x32_bf16 v[18:21], v[34:37], v[90:93], 0
	v_mfma_f32_16x16x32_bf16 v[32:35], v[38:41], v[94:97], v[18:21]
	v_mfma_f32_16x16x32_bf16 v[18:21], v[42:45], v[82:85], 0
	v_mfma_f32_16x16x32_bf16 v[36:39], v[46:49], v[86:89], v[18:21]
	v_mfma_f32_16x16x32_bf16 v[18:21], v[42:45], v[90:93], 0
	v_mfma_f32_16x16x32_bf16 v[98:101], v[22:25], v[86:89], v[98:101]
	v_mfma_f32_16x16x32_bf16 v[118:121], v[46:49], v[94:97], v[18:21]
	s_setprio 0
	s_mov_b32 m0, s44
	s_barrier
	s_nop 2
	ds_read_b128 v[18:21], v131 offset:16384
	ds_read_b128 v[22:25], v131 offset:17408
	ds_read_b128 v[26:29], v137 offset:16384
	ds_read_b128 v[40:43], v137 offset:17408
	ds_read_b128 v[44:47], v138 offset:16384
	ds_read_b128 v[122:125], v138 offset:17408
	ds_read_b128 v[142:145], v139 offset:16384
	ds_read_b128 v[146:149], v139 offset:17408
	buffer_load_dwordx4 v128, s[4:7], s28 offen lds
	s_mov_b32 m0, s47
	s_nop 0
	buffer_load_dwordx4 v128, s[4:7], s30 offen lds
	s_barrier
	s_waitcnt lgkmcnt(0)
	s_setprio 1
	s_waitcnt lgkmcnt(7)
	v_mfma_f32_16x16x32_bf16 v[150:153], v[18:21], v[2:5], 0
	s_waitcnt lgkmcnt(5)
	v_mfma_f32_16x16x32_bf16 v[158:161], v[26:29], v[2:5], 0
	s_waitcnt lgkmcnt(3)
	v_mfma_f32_16x16x32_bf16 v[166:169], v[44:47], v[2:5], 0
	s_waitcnt lgkmcnt(1)
	v_mfma_f32_16x16x32_bf16 v[0:3], v[142:145], v[2:5], 0
	v_mfma_f32_16x16x32_bf16 v[154:157], v[18:21], v[10:13], 0
	v_mfma_f32_16x16x32_bf16 v[162:165], v[26:29], v[10:13], 0
	v_mfma_f32_16x16x32_bf16 v[170:173], v[44:47], v[10:13], 0
	s_waitcnt lgkmcnt(0)
	v_mfma_f32_16x16x32_bf16 v[174:177], v[146:149], v[6:9], v[0:3]
	v_mfma_f32_16x16x32_bf16 v[0:3], v[142:145], v[10:13], 0
	v_mfma_f32_16x16x32_bf16 v[150:153], v[22:25], v[6:9], v[150:153]
	v_mfma_f32_16x16x32_bf16 v[154:157], v[22:25], v[14:17], v[154:157]
	v_mfma_f32_16x16x32_bf16 v[158:161], v[40:43], v[6:9], v[158:161]
	v_mfma_f32_16x16x32_bf16 v[162:165], v[40:43], v[14:17], v[162:165]
	v_mfma_f32_16x16x32_bf16 v[166:169], v[122:125], v[6:9], v[166:169]
	v_mfma_f32_16x16x32_bf16 v[170:173], v[122:125], v[14:17], v[170:173]
	v_mfma_f32_16x16x32_bf16 v[178:181], v[146:149], v[14:17], v[0:3]
	s_setprio 0
	s_barrier
	s_mov_b32 m0, s48
	s_nop 0
	buffer_load_dwordx4 v130, s[8:11], s31 offen lds
	s_mov_b32 m0, s49
	s_nop 0
	buffer_load_dwordx4 v130, s[8:11], s34 offen lds
	s_waitcnt vmcnt(6)
	s_barrier
	s_setprio 1
	v_mfma_f32_16x16x32_bf16 v[0:3], v[18:21], v[82:85], 0
	v_mfma_f32_16x16x32_bf16 v[182:185], v[22:25], v[86:89], v[0:3]
	v_mfma_f32_16x16x32_bf16 v[0:3], v[18:21], v[90:93], 0
	v_mfma_f32_16x16x32_bf16 v[186:189], v[22:25], v[94:97], v[0:3]
	v_mfma_f32_16x16x32_bf16 v[0:3], v[26:29], v[82:85], 0
	v_mfma_f32_16x16x32_bf16 v[190:193], v[40:43], v[86:89], v[0:3]
	v_mfma_f32_16x16x32_bf16 v[0:3], v[26:29], v[90:93], 0
	v_mfma_f32_16x16x32_bf16 v[194:197], v[40:43], v[94:97], v[0:3]
	v_mfma_f32_16x16x32_bf16 v[0:3], v[44:47], v[82:85], 0
	v_mfma_f32_16x16x32_bf16 v[198:201], v[122:125], v[86:89], v[0:3]
	v_mfma_f32_16x16x32_bf16 v[0:3], v[44:47], v[90:93], 0
	v_mfma_f32_16x16x32_bf16 v[202:205], v[122:125], v[94:97], v[0:3]
	v_mfma_f32_16x16x32_bf16 v[0:3], v[142:145], v[82:85], 0
	v_mfma_f32_16x16x32_bf16 v[206:209], v[146:149], v[86:89], v[0:3]
	v_mfma_f32_16x16x32_bf16 v[0:3], v[142:145], v[90:93], 0
	v_mfma_f32_16x16x32_bf16 v[144:147], v[146:149], v[94:97], v[0:3]
	s_setprio 0
	s_nop 5
	v_add_u32_e32 v0, s97, v127
	v_add_u32_e32 v142, v0, v126
	s_barrier
	ds_read_b128 v[122:125], v142
	ds_read_b128 v[210:213], v142 offset:1024
	ds_read_b128 v[214:217], v142 offset:2048
	ds_read_b128 v[218:221], v142 offset:3072
	s_mov_b32 m0, s52
	ds_read_b128 v[40:43], v131 offset:32768
	ds_read_b128 v[44:47], v131 offset:33792
	ds_read_b128 v[82:85], v137 offset:32768
	ds_read_b128 v[86:89], v137 offset:33792
	ds_read_b128 v[90:93], v138 offset:32768
	ds_read_b128 v[94:97], v138 offset:33792
	ds_read_b128 v[222:225], v139 offset:32768
	ds_read_b128 v[226:229], v139 offset:33792
	buffer_load_dwordx4 v128, s[4:7], s35 offen lds
	s_mov_b32 m0, s53
	s_nop 0
	buffer_load_dwordx4 v128, s[4:7], s36 offen lds
	s_waitcnt lgkmcnt(8)
	s_barrier
	s_waitcnt lgkmcnt(0)
	s_setprio 1
	s_waitcnt lgkmcnt(7)
	v_mfma_f32_16x16x32_bf16 v[0:3], v[40:43], v[122:125], v[50:53]
	s_waitcnt lgkmcnt(6)
	v_mfma_f32_16x16x32_bf16 v[28:31], v[44:47], v[210:213], v[0:3]
	v_mfma_f32_16x16x32_bf16 v[0:3], v[40:43], v[214:217], v[54:57]
	v_mfma_f32_16x16x32_bf16 v[24:27], v[44:47], v[218:221], v[0:3]
	s_waitcnt lgkmcnt(5)
	v_mfma_f32_16x16x32_bf16 v[0:3], v[82:85], v[122:125], v[58:61]
	s_waitcnt lgkmcnt(4)
	v_mfma_f32_16x16x32_bf16 v[20:23], v[86:89], v[210:213], v[0:3]
	v_mfma_f32_16x16x32_bf16 v[0:3], v[82:85], v[214:217], v[62:65]
	v_mfma_f32_16x16x32_bf16 v[16:19], v[86:89], v[218:221], v[0:3]
	s_waitcnt lgkmcnt(3)
	v_mfma_f32_16x16x32_bf16 v[0:3], v[90:93], v[122:125], v[66:69]
	s_waitcnt lgkmcnt(2)
	v_mfma_f32_16x16x32_bf16 v[12:15], v[94:97], v[210:213], v[0:3]
	v_mfma_f32_16x16x32_bf16 v[0:3], v[90:93], v[214:217], v[70:73]
	v_mfma_f32_16x16x32_bf16 v[8:11], v[94:97], v[218:221], v[0:3]
	s_waitcnt lgkmcnt(1)
	v_mfma_f32_16x16x32_bf16 v[0:3], v[222:225], v[122:125], v[74:77]
	s_waitcnt lgkmcnt(0)
	v_mfma_f32_16x16x32_bf16 v[4:7], v[226:229], v[210:213], v[0:3]
	v_mfma_f32_16x16x32_bf16 v[0:3], v[222:225], v[214:217], v[78:81]
	v_mfma_f32_16x16x32_bf16 v[0:3], v[226:229], v[218:221], v[0:3]
	s_setprio 0
	s_barrier
	v_add_u32_e32 v48, s68, v127
	v_add_u32_e32 v143, v48, v126
	s_mov_b32 m0, s2
	ds_read_b128 v[230:233], v143
	ds_read_b128 v[234:237], v143 offset:1024
	ds_read_b128 v[238:241], v143 offset:2048
	ds_read_b128 v[242:245], v143 offset:3072
	buffer_load_dwordx4 v130, s[8:11], s37 offen lds
	s_mov_b32 m0, s3
	s_nop 0
	buffer_load_dwordx4 v130, s[8:11], s38 offen lds
	s_barrier
	s_waitcnt lgkmcnt(0)
	s_setprio 1
	s_waitcnt lgkmcnt(3)
	v_mfma_f32_16x16x32_bf16 v[48:51], v[40:43], v[230:233], v[98:101]
	s_waitcnt lgkmcnt(1)
	v_mfma_f32_16x16x32_bf16 v[40:43], v[40:43], v[238:241], v[102:105]
	s_waitcnt lgkmcnt(0)
	v_mfma_f32_16x16x32_bf16 v[56:59], v[44:47], v[242:245], v[40:43]
	v_mfma_f32_16x16x32_bf16 v[40:43], v[82:85], v[230:233], v[106:109]
	v_mfma_f32_16x16x32_bf16 v[52:55], v[86:89], v[234:237], v[40:43]
	v_mfma_f32_16x16x32_bf16 v[40:43], v[82:85], v[238:241], v[110:113]
	v_mfma_f32_16x16x32_bf16 v[60:63], v[44:47], v[234:237], v[48:51]
	v_mfma_f32_16x16x32_bf16 v[48:51], v[86:89], v[242:245], v[40:43]
	v_mfma_f32_16x16x32_bf16 v[40:43], v[90:93], v[230:233], v[114:117]
	v_mfma_f32_16x16x32_bf16 v[32:35], v[90:93], v[238:241], v[32:35]
	v_mfma_f32_16x16x32_bf16 v[44:47], v[94:97], v[234:237], v[40:43]
	v_mfma_f32_16x16x32_bf16 v[40:43], v[94:97], v[242:245], v[32:35]
	v_mfma_f32_16x16x32_bf16 v[32:35], v[222:225], v[230:233], v[36:39]
	v_mfma_f32_16x16x32_bf16 v[36:39], v[226:229], v[234:237], v[32:35]
	v_mfma_f32_16x16x32_bf16 v[32:35], v[222:225], v[238:241], v[118:121]
	v_mfma_f32_16x16x32_bf16 v[32:35], v[226:229], v[242:245], v[32:35]
	s_setprio 0
	s_mov_b32 m0, s66
	s_barrier
	ds_read_b128 v[96:99], v131 offset:49152
	ds_read_b128 v[100:103], v131 offset:50176
	ds_read_b128 v[104:107], v137 offset:49152
	ds_read_b128 v[108:111], v137 offset:50176
	ds_read_b128 v[222:225], v138 offset:49152
	ds_read_b128 v[226:229], v138 offset:50176
	ds_read_b128 v[246:249], v139 offset:49152
	ds_read_b128 v[250:253], v139 offset:50176
	buffer_load_dwordx4 v128, s[4:7], s37 offen lds
	s_mov_b32 m0, s67
	s_nop 0
	buffer_load_dwordx4 v128, s[4:7], s39 offen lds
	s_barrier
	s_waitcnt lgkmcnt(0)
	s_setprio 1
	s_waitcnt lgkmcnt(7)
	v_mfma_f32_16x16x32_bf16 v[64:67], v[96:99], v[122:125], v[150:153]
	s_waitcnt lgkmcnt(6)
	v_mfma_f32_16x16x32_bf16 v[92:95], v[100:103], v[210:213], v[64:67]
	v_mfma_f32_16x16x32_bf16 v[64:67], v[96:99], v[214:217], v[154:157]
	v_mfma_f32_16x16x32_bf16 v[88:91], v[100:103], v[218:221], v[64:67]
	s_waitcnt lgkmcnt(5)
	v_mfma_f32_16x16x32_bf16 v[64:67], v[104:107], v[122:125], v[158:161]
	s_waitcnt lgkmcnt(4)
	v_mfma_f32_16x16x32_bf16 v[84:87], v[108:111], v[210:213], v[64:67]
	v_mfma_f32_16x16x32_bf16 v[64:67], v[104:107], v[214:217], v[162:165]
	v_mfma_f32_16x16x32_bf16 v[80:83], v[108:111], v[218:221], v[64:67]
	s_waitcnt lgkmcnt(3)
	v_mfma_f32_16x16x32_bf16 v[64:67], v[222:225], v[122:125], v[166:169]
	s_waitcnt lgkmcnt(2)
	v_mfma_f32_16x16x32_bf16 v[76:79], v[226:229], v[210:213], v[64:67]
	v_mfma_f32_16x16x32_bf16 v[64:67], v[222:225], v[214:217], v[170:173]
	v_mfma_f32_16x16x32_bf16 v[72:75], v[226:229], v[218:221], v[64:67]
	s_waitcnt lgkmcnt(1)
	v_mfma_f32_16x16x32_bf16 v[64:67], v[246:249], v[122:125], v[174:177]
	s_waitcnt lgkmcnt(0)
	v_mfma_f32_16x16x32_bf16 v[68:71], v[250:253], v[210:213], v[64:67]
	v_mfma_f32_16x16x32_bf16 v[64:67], v[246:249], v[214:217], v[178:181]
	v_mfma_f32_16x16x32_bf16 v[64:67], v[250:253], v[218:221], v[64:67]
	s_setprio 0
	s_barrier
	s_mov_b32 m0, s78
	s_nop 0
	buffer_load_dwordx4 v130, s[8:11], s40 offen lds
	s_mov_b32 m0, s79
	s_nop 0
	buffer_load_dwordx4 v130, s[8:11], s41 offen lds
	s_waitcnt vmcnt(6)
	s_barrier
	s_setprio 1
	v_mfma_f32_16x16x32_bf16 v[112:115], v[96:99], v[230:233], v[182:185]
	v_mfma_f32_16x16x32_bf16 v[96:99], v[96:99], v[238:241], v[186:189]
	v_mfma_f32_16x16x32_bf16 v[120:123], v[100:103], v[242:245], v[96:99]
	v_mfma_f32_16x16x32_bf16 v[96:99], v[104:107], v[230:233], v[190:193]
	v_mfma_f32_16x16x32_bf16 v[116:119], v[108:111], v[234:237], v[96:99]
	v_mfma_f32_16x16x32_bf16 v[96:99], v[104:107], v[238:241], v[194:197]
	v_mfma_f32_16x16x32_bf16 v[124:127], v[100:103], v[234:237], v[112:115]
	v_mfma_f32_16x16x32_bf16 v[112:115], v[108:111], v[242:245], v[96:99]
	v_mfma_f32_16x16x32_bf16 v[96:99], v[222:225], v[230:233], v[198:201]
	v_mfma_f32_16x16x32_bf16 v[108:111], v[226:229], v[234:237], v[96:99]
	v_mfma_f32_16x16x32_bf16 v[96:99], v[222:225], v[238:241], v[202:205]
	v_mfma_f32_16x16x32_bf16 v[104:107], v[226:229], v[242:245], v[96:99]
	v_mfma_f32_16x16x32_bf16 v[96:99], v[246:249], v[230:233], v[206:209]
	v_mfma_f32_16x16x32_bf16 v[100:103], v[250:253], v[234:237], v[96:99]
	v_mfma_f32_16x16x32_bf16 v[96:99], v[246:249], v[238:241], v[144:147]
	v_mfma_f32_16x16x32_bf16 v[96:99], v[250:253], v[242:245], v[96:99]
	s_setprio 0
	s_mov_b32 s83, 0
	s_mov_b32 s84, 0x180200
	s_barrier
